# more cache hints: nt on z-path Z stores and on read-once job input loads in phases 2-3 (on top of v34 hints)
# speedup vs baseline: 1.0147x; 1.0147x over previous
.LBB0_272:
	s_or_b64 exec, exec, s[14:15]
	v_lshlrev_b64 v[58:59], 11, v[28:29]
	v_or_b32_e32 v58, v58, v26
	v_lshl_add_u64 v[50:51], s[34:35], 0, v[58:59]
	global_load_dwordx4 v[50:53], v[50:51], off nt
	v_lshl_add_u64 v[54:55], s[4:5], 0, v[58:59]
	global_load_dwordx4 v[54:57], v[54:55], off nt
	s_waitcnt vmcnt(0)
	v_pk_mul_f32 v[44:45], v[16:17], v[44:45]
	v_pk_mul_f32 v[42:43], v[14:15], v[42:43]
	v_pk_mul_f32 v[40:41], v[10:11], v[40:41]
	v_pk_mul_f32 v[38:39], v[12:13], v[38:39]
	v_or_b32_e32 v60, 1, v28
	v_pk_fma_f32 v[44:45], v[24:25], v[36:37], v[44:45]
	v_pk_fma_f32 v[42:43], v[22:23], v[32:33], v[42:43]
	v_pk_fma_f32 v[38:39], v[20:21], v[34:35], v[38:39]
	v_pk_fma_f32 v[40:41], v[18:19], v[30:31], v[40:41]
	v_ashrrev_i32_e32 v61, 31, v60
	v_lshlrev_b64 v[60:61], 11, v[60:61]
	v_lshl_add_u64 v[58:59], s[6:7], 0, v[58:59]
	v_or_b32_e32 v60, v60, v26
	v_lshl_add_u64 v[62:63], s[34:35], 0, v[60:61]
	v_add_u32_e32 v46, s16, v46
	v_cmp_lt_i32_e32 vcc, s17, v46
	s_or_b64 s[12:13], vcc, s[12:13]
	v_add_u32_e32 v47, s2, v47
	v_lshlrev_b32_e32 v64, 16, v50
	v_and_b32_e32 v65, 0xffff0000, v50
	v_lshlrev_b32_e32 v50, 16, v51
	v_and_b32_e32 v51, 0xffff0000, v51
	v_lshlrev_b32_e32 v66, 16, v52
	v_and_b32_e32 v67, 0xffff0000, v52
	v_lshlrev_b32_e32 v52, 16, v53
	v_and_b32_e32 v53, 0xffff0000, v53
	v_lshlrev_b32_e32 v68, 16, v54
	v_and_b32_e32 v69, 0xffff0000, v54
	v_lshlrev_b32_e32 v54, 16, v55
	v_and_b32_e32 v55, 0xffff0000, v55
	v_lshlrev_b32_e32 v70, 16, v56
	v_and_b32_e32 v71, 0xffff0000, v56
	v_lshlrev_b32_e32 v56, 16, v57
	v_and_b32_e32 v57, 0xffff0000, v57
	v_pk_fma_f32 v[42:43], v[6:7], v[64:65], v[42:43]
	v_pk_fma_f32 v[44:45], v[8:9], v[50:51], v[44:45]
	v_pk_fma_f32 v[40:41], v[2:3], v[66:67], v[40:41]
	v_pk_fma_f32 v[38:39], v[4:5], v[52:53], v[38:39]
	v_pk_mul_f32 v[44:45], v[44:45], v[54:55]
	v_pk_mul_f32 v[42:43], v[42:43], v[68:69]
	v_pk_mul_f32 v[54:55], v[38:39], v[56:57]
	v_pk_mul_f32 v[40:41], v[40:41], v[70:71]
	v_cvt_pk_bf16_f32 v38, v42, v43
	v_cvt_pk_bf16_f32 v39, v44, v45
	v_cvt_pk_bf16_f32 v40, v40, v41
	v_cvt_pk_bf16_f32 v41, v54, v55
	global_store_dwordx4 v[58:59], v[38:41], off nt
	global_load_dwordx4 v[38:41], v[62:63], off nt
	v_lshl_add_u64 v[42:43], s[4:5], 0, v[60:61]
	global_load_dwordx4 v[42:45], v[42:43], off nt
	v_lshl_add_u64 v[56:57], s[6:7], 0, v[60:61]
	v_pk_mul_f32 v[60:61], v[22:23], v[64:65]
	v_pk_mul_f32 v[62:63], v[24:25], v[50:51]
	v_pk_mul_f32 v[68:69], v[18:19], v[66:67]
	v_pk_mul_f32 v[70:71], v[20:21], v[52:53]
	v_or_b32_e32 v54, 2, v28
	v_pk_fma_f32 v[36:37], v[16:17], v[36:37], v[62:63]
	v_pk_fma_f32 v[32:33], v[14:15], v[32:33], v[60:61]
	v_pk_fma_f32 v[34:35], v[12:13], v[34:35], v[70:71]
	v_pk_fma_f32 v[30:31], v[10:11], v[30:31], v[68:69]
	v_ashrrev_i32_e32 v55, 31, v54
	v_lshlrev_b64 v[54:55], 11, v[54:55]
	v_or_b32_e32 v54, v54, v26
	v_lshl_add_u64 v[58:59], s[34:35], 0, v[54:55]
	s_waitcnt vmcnt(1)
	v_lshlrev_b32_e32 v60, 16, v38
	v_and_b32_e32 v61, 0xffff0000, v38
	v_lshlrev_b32_e32 v38, 16, v39
	v_and_b32_e32 v39, 0xffff0000, v39
	v_lshlrev_b32_e32 v62, 16, v40
	v_and_b32_e32 v63, 0xffff0000, v40
	v_lshlrev_b32_e32 v40, 16, v41
	v_and_b32_e32 v41, 0xffff0000, v41
	s_waitcnt vmcnt(0)
	v_lshlrev_b32_e32 v68, 16, v42
	v_and_b32_e32 v69, 0xffff0000, v42
	v_lshlrev_b32_e32 v42, 16, v43
	v_and_b32_e32 v43, 0xffff0000, v43
	v_lshlrev_b32_e32 v70, 16, v44
	v_and_b32_e32 v71, 0xffff0000, v44
	v_lshlrev_b32_e32 v44, 16, v45
	v_and_b32_e32 v45, 0xffff0000, v45
	v_pk_fma_f32 v[32:33], v[6:7], v[60:61], v[32:33]
	v_pk_fma_f32 v[36:37], v[8:9], v[38:39], v[36:37]
	v_pk_fma_f32 v[30:31], v[2:3], v[62:63], v[30:31]
	v_pk_fma_f32 v[34:35], v[4:5], v[40:41], v[34:35]
	v_pk_mul_f32 v[36:37], v[36:37], v[42:43]
	v_pk_mul_f32 v[32:33], v[32:33], v[68:69]
	v_pk_mul_f32 v[34:35], v[34:35], v[44:45]
	v_pk_mul_f32 v[42:43], v[30:31], v[70:71]
	v_cvt_pk_bf16_f32 v30, v32, v33
	v_cvt_pk_bf16_f32 v31, v36, v37
	v_cvt_pk_bf16_f32 v32, v42, v43
	v_cvt_pk_bf16_f32 v33, v34, v35
	global_store_dwordx4 v[56:57], v[30:33], off nt
	global_load_dwordx4 v[30:33], v[58:59], off nt
	v_lshl_add_u64 v[34:35], s[4:5], 0, v[54:55]
	global_load_dwordx4 v[34:37], v[34:35], off nt
	v_pk_mul_f32 v[56:57], v[22:23], v[60:61]
	v_pk_mul_f32 v[58:59], v[24:25], v[38:39]
	v_pk_mul_f32 v[68:69], v[18:19], v[62:63]
	v_pk_mul_f32 v[70:71], v[20:21], v[40:41]
	v_or_b32_e32 v42, 3, v28
	v_pk_fma_f32 v[50:51], v[16:17], v[50:51], v[58:59]
	v_pk_fma_f32 v[56:57], v[14:15], v[64:65], v[56:57]
	v_pk_fma_f32 v[52:53], v[12:13], v[52:53], v[70:71]
	v_pk_fma_f32 v[58:59], v[10:11], v[66:67], v[68:69]
	v_ashrrev_i32_e32 v43, 31, v42
	v_lshlrev_b64 v[42:43], 11, v[42:43]
	v_or_b32_e32 v42, v42, v26
	v_lshl_add_u64 v[44:45], s[6:7], 0, v[54:55]
	v_lshl_add_u64 v[54:55], s[34:35], 0, v[42:43]
	s_waitcnt vmcnt(1)
	v_lshlrev_b32_e32 v64, 16, v30
	v_and_b32_e32 v65, 0xffff0000, v30
	v_lshlrev_b32_e32 v66, 16, v31
	v_and_b32_e32 v67, 0xffff0000, v31
	v_lshlrev_b32_e32 v68, 16, v32
	v_and_b32_e32 v69, 0xffff0000, v32
	v_lshlrev_b32_e32 v70, 16, v33
	v_and_b32_e32 v71, 0xffff0000, v33
	s_waitcnt vmcnt(0)
	v_lshlrev_b32_e32 v30, 16, v34
	v_and_b32_e32 v31, 0xffff0000, v34
	v_lshlrev_b32_e32 v32, 16, v35
	v_and_b32_e32 v33, 0xffff0000, v35
	v_lshlrev_b32_e32 v34, 16, v36
	v_and_b32_e32 v35, 0xffff0000, v36
	v_lshlrev_b32_e32 v36, 16, v37
	v_and_b32_e32 v37, 0xffff0000, v37
	v_pk_fma_f32 v[56:57], v[6:7], v[64:65], v[56:57]
	v_pk_fma_f32 v[50:51], v[8:9], v[66:67], v[50:51]
	v_pk_fma_f32 v[58:59], v[2:3], v[68:69], v[58:59]
	v_pk_fma_f32 v[52:53], v[4:5], v[70:71], v[52:53]
	v_pk_mul_f32 v[32:33], v[50:51], v[32:33]
	v_pk_mul_f32 v[30:31], v[56:57], v[30:31]
	v_pk_mul_f32 v[36:37], v[52:53], v[36:37]
	v_pk_mul_f32 v[34:35], v[58:59], v[34:35]
	v_cvt_pk_bf16_f32 v30, v30, v31
	v_cvt_pk_bf16_f32 v31, v32, v33
	v_cvt_pk_bf16_f32 v32, v34, v35
	v_cvt_pk_bf16_f32 v33, v36, v37
	global_store_dwordx4 v[44:45], v[30:33], off nt
	global_load_dwordx4 v[30:33], v[54:55], off nt
	v_lshl_add_u64 v[34:35], s[4:5], 0, v[42:43]
	global_load_dwordx4 v[34:37], v[34:35], off nt
	v_pk_mul_f32 v[52:53], v[22:23], v[64:65]
	v_pk_mul_f32 v[54:55], v[24:25], v[66:67]
	v_pk_mul_f32 v[56:57], v[18:19], v[68:69]
	v_pk_mul_f32 v[58:59], v[20:21], v[70:71]
	v_or_b32_e32 v44, 4, v28
	v_pk_fma_f32 v[38:39], v[16:17], v[38:39], v[54:55]
	v_pk_fma_f32 v[52:53], v[14:15], v[60:61], v[52:53]
	v_pk_fma_f32 v[40:41], v[12:13], v[40:41], v[58:59]
	v_pk_fma_f32 v[54:55], v[10:11], v[62:63], v[56:57]
	v_ashrrev_i32_e32 v45, 31, v44
	v_lshlrev_b64 v[44:45], 11, v[44:45]
	v_or_b32_e32 v44, v44, v26
	v_lshl_add_u64 v[42:43], s[6:7], 0, v[42:43]
	v_lshl_add_u64 v[50:51], s[34:35], 0, v[44:45]
	s_waitcnt vmcnt(1)
	v_lshlrev_b32_e32 v56, 16, v30
	v_and_b32_e32 v57, 0xffff0000, v30
	v_lshlrev_b32_e32 v58, 16, v31
	v_and_b32_e32 v59, 0xffff0000, v31
	v_lshlrev_b32_e32 v60, 16, v32
	v_and_b32_e32 v61, 0xffff0000, v32
	v_lshlrev_b32_e32 v62, 16, v33
	v_and_b32_e32 v63, 0xffff0000, v33
	s_waitcnt vmcnt(0)
	v_lshlrev_b32_e32 v30, 16, v34
	v_and_b32_e32 v31, 0xffff0000, v34
	v_lshlrev_b32_e32 v32, 16, v35
	v_and_b32_e32 v33, 0xffff0000, v35
	v_lshlrev_b32_e32 v34, 16, v36
	v_and_b32_e32 v35, 0xffff0000, v36
	v_lshlrev_b32_e32 v36, 16, v37
	v_and_b32_e32 v37, 0xffff0000, v37
	v_pk_fma_f32 v[52:53], v[6:7], v[56:57], v[52:53]
	v_pk_fma_f32 v[38:39], v[8:9], v[58:59], v[38:39]
	v_pk_fma_f32 v[54:55], v[2:3], v[60:61], v[54:55]
	v_pk_fma_f32 v[40:41], v[4:5], v[62:63], v[40:41]
	v_pk_mul_f32 v[32:33], v[38:39], v[32:33]
	v_pk_mul_f32 v[30:31], v[52:53], v[30:31]
	v_pk_mul_f32 v[36:37], v[40:41], v[36:37]
	v_pk_mul_f32 v[34:35], v[54:55], v[34:35]
	v_cvt_pk_bf16_f32 v30, v30, v31
	v_cvt_pk_bf16_f32 v31, v32, v33
	v_cvt_pk_bf16_f32 v32, v34, v35
	v_cvt_pk_bf16_f32 v33, v36, v37
	global_store_dwordx4 v[42:43], v[30:33], off nt
	global_load_dwordx4 v[30:33], v[50:51], off nt
	v_lshl_add_u64 v[34:35], s[4:5], 0, v[44:45]
	global_load_dwordx4 v[34:37], v[34:35], off nt
	v_lshl_add_u64 v[40:41], s[6:7], 0, v[44:45]
	v_pk_mul_f32 v[44:45], v[22:23], v[56:57]
	v_pk_mul_f32 v[50:51], v[24:25], v[58:59]
	v_pk_mul_f32 v[52:53], v[18:19], v[60:61]
	v_pk_mul_f32 v[54:55], v[20:21], v[62:63]
	v_or_b32_e32 v38, 5, v28
	v_pk_fma_f32 v[50:51], v[16:17], v[66:67], v[50:51]
	v_pk_fma_f32 v[44:45], v[14:15], v[64:65], v[44:45]
	v_pk_fma_f32 v[54:55], v[12:13], v[70:71], v[54:55]
	v_pk_fma_f32 v[52:53], v[10:11], v[68:69], v[52:53]
	v_ashrrev_i32_e32 v39, 31, v38
	v_lshlrev_b64 v[38:39], 11, v[38:39]
	v_or_b32_e32 v38, v38, v26
	v_lshl_add_u64 v[42:43], s[34:35], 0, v[38:39]
	s_waitcnt vmcnt(1)
	v_lshlrev_b32_e32 v64, 16, v30
	v_and_b32_e32 v65, 0xffff0000, v30
	v_lshlrev_b32_e32 v66, 16, v31
	v_and_b32_e32 v67, 0xffff0000, v31
	v_lshlrev_b32_e32 v68, 16, v32
	v_and_b32_e32 v69, 0xffff0000, v32
	v_lshlrev_b32_e32 v70, 16, v33
	v_and_b32_e32 v71, 0xffff0000, v33
	s_waitcnt vmcnt(0)
	v_lshlrev_b32_e32 v30, 16, v34
	v_and_b32_e32 v31, 0xffff0000, v34
	v_lshlrev_b32_e32 v32, 16, v35
	v_and_b32_e32 v33, 0xffff0000, v35
	v_lshlrev_b32_e32 v34, 16, v36
	v_and_b32_e32 v35, 0xffff0000, v36
	v_lshlrev_b32_e32 v36, 16, v37
	v_and_b32_e32 v37, 0xffff0000, v37
	v_pk_fma_f32 v[44:45], v[6:7], v[64:65], v[44:45]
	v_pk_fma_f32 v[50:51], v[8:9], v[66:67], v[50:51]
	v_pk_fma_f32 v[52:53], v[2:3], v[68:69], v[52:53]
	v_pk_fma_f32 v[54:55], v[4:5], v[70:71], v[54:55]
	v_pk_mul_f32 v[32:33], v[50:51], v[32:33]
	v_pk_mul_f32 v[30:31], v[44:45], v[30:31]
	v_pk_mul_f32 v[36:37], v[54:55], v[36:37]
	v_pk_mul_f32 v[34:35], v[52:53], v[34:35]
	v_cvt_pk_bf16_f32 v30, v30, v31
	v_cvt_pk_bf16_f32 v31, v32, v33
	v_cvt_pk_bf16_f32 v32, v34, v35
	v_cvt_pk_bf16_f32 v33, v36, v37
	global_store_dwordx4 v[40:41], v[30:33], off nt
	global_load_dwordx4 v[30:33], v[42:43], off nt
	v_lshl_add_u64 v[34:35], s[4:5], 0, v[38:39]
	global_load_dwordx4 v[34:37], v[34:35], off nt
	v_pk_mul_f32 v[44:45], v[22:23], v[64:65]
	v_pk_mul_f32 v[50:51], v[24:25], v[66:67]
	v_pk_mul_f32 v[52:53], v[18:19], v[68:69]
	v_pk_mul_f32 v[54:55], v[20:21], v[70:71]
	v_or_b32_e32 v40, 6, v28
	v_pk_fma_f32 v[50:51], v[16:17], v[58:59], v[50:51]
	v_pk_fma_f32 v[44:45], v[14:15], v[56:57], v[44:45]
	v_pk_fma_f32 v[54:55], v[12:13], v[62:63], v[54:55]
	v_pk_fma_f32 v[52:53], v[10:11], v[60:61], v[52:53]
	v_ashrrev_i32_e32 v41, 31, v40
	v_lshlrev_b64 v[40:41], 11, v[40:41]
	v_or_b32_e32 v40, v40, v26
	v_lshl_add_u64 v[38:39], s[6:7], 0, v[38:39]
	v_lshl_add_u64 v[42:43], s[34:35], 0, v[40:41]
	s_waitcnt vmcnt(1)
	v_lshlrev_b32_e32 v56, 16, v30
	v_and_b32_e32 v57, 0xffff0000, v30
	v_lshlrev_b32_e32 v58, 16, v31
	v_and_b32_e32 v59, 0xffff0000, v31
	v_lshlrev_b32_e32 v60, 16, v32
	v_and_b32_e32 v61, 0xffff0000, v32
	v_lshlrev_b32_e32 v62, 16, v33
	v_and_b32_e32 v63, 0xffff0000, v33
	s_waitcnt vmcnt(0)
	v_lshlrev_b32_e32 v30, 16, v34
	v_and_b32_e32 v31, 0xffff0000, v34
	v_lshlrev_b32_e32 v32, 16, v35
	v_and_b32_e32 v33, 0xffff0000, v35
	v_lshlrev_b32_e32 v34, 16, v36
	v_and_b32_e32 v35, 0xffff0000, v36
	v_lshlrev_b32_e32 v36, 16, v37
	v_and_b32_e32 v37, 0xffff0000, v37
	v_pk_fma_f32 v[44:45], v[6:7], v[56:57], v[44:45]
	v_pk_fma_f32 v[50:51], v[8:9], v[58:59], v[50:51]
	v_pk_fma_f32 v[52:53], v[2:3], v[60:61], v[52:53]
	v_pk_fma_f32 v[54:55], v[4:5], v[62:63], v[54:55]
	v_pk_mul_f32 v[32:33], v[50:51], v[32:33]
	v_pk_mul_f32 v[30:31], v[44:45], v[30:31]
	v_pk_mul_f32 v[36:37], v[54:55], v[36:37]
	v_pk_mul_f32 v[34:35], v[52:53], v[34:35]
	v_cvt_pk_bf16_f32 v30, v30, v31
	v_cvt_pk_bf16_f32 v31, v32, v33
	v_cvt_pk_bf16_f32 v32, v34, v35
	v_cvt_pk_bf16_f32 v33, v36, v37
	global_store_dwordx4 v[38:39], v[30:33], off nt
	global_load_dwordx4 v[30:33], v[42:43], off nt
	v_lshl_add_u64 v[34:35], s[4:5], 0, v[40:41]
	global_load_dwordx4 v[34:37], v[34:35], off nt
	v_pk_mul_f32 v[44:45], v[22:23], v[56:57]
	v_pk_mul_f32 v[50:51], v[24:25], v[58:59]
	v_pk_mul_f32 v[52:53], v[18:19], v[60:61]
	v_pk_mul_f32 v[54:55], v[20:21], v[62:63]
	v_or_b32_e32 v38, 7, v28
	v_pk_fma_f32 v[50:51], v[16:17], v[66:67], v[50:51]
	v_pk_fma_f32 v[44:45], v[14:15], v[64:65], v[44:45]
	v_pk_fma_f32 v[54:55], v[12:13], v[70:71], v[54:55]
	v_pk_fma_f32 v[52:53], v[10:11], v[68:69], v[52:53]
	v_ashrrev_i32_e32 v39, 31, v38
	v_lshlrev_b64 v[38:39], 11, v[38:39]
	v_or_b32_e32 v38, v38, v26
	v_lshl_add_u64 v[40:41], s[6:7], 0, v[40:41]
	v_lshl_add_u64 v[42:43], s[34:35], 0, v[38:39]
	s_waitcnt vmcnt(1)
	v_lshlrev_b32_e32 v64, 16, v30
	v_and_b32_e32 v65, 0xffff0000, v30
	v_lshlrev_b32_e32 v66, 16, v31
	v_and_b32_e32 v67, 0xffff0000, v31
	v_lshlrev_b32_e32 v68, 16, v32
	v_and_b32_e32 v69, 0xffff0000, v32
	v_lshlrev_b32_e32 v70, 16, v33
	v_and_b32_e32 v71, 0xffff0000, v33
	s_waitcnt vmcnt(0)
	v_lshlrev_b32_e32 v30, 16, v34
	v_and_b32_e32 v31, 0xffff0000, v34
	v_lshlrev_b32_e32 v32, 16, v35
	v_and_b32_e32 v33, 0xffff0000, v35
	v_lshlrev_b32_e32 v34, 16, v36
	v_and_b32_e32 v35, 0xffff0000, v36
	v_lshlrev_b32_e32 v36, 16, v37
	v_and_b32_e32 v37, 0xffff0000, v37
	v_pk_fma_f32 v[44:45], v[6:7], v[64:65], v[44:45]
	v_pk_fma_f32 v[50:51], v[8:9], v[66:67], v[50:51]
	v_pk_fma_f32 v[52:53], v[2:3], v[68:69], v[52:53]
	v_pk_fma_f32 v[54:55], v[4:5], v[70:71], v[54:55]
	v_pk_mul_f32 v[32:33], v[50:51], v[32:33]
	v_pk_mul_f32 v[30:31], v[44:45], v[30:31]
	v_pk_mul_f32 v[36:37], v[54:55], v[36:37]
	v_pk_mul_f32 v[34:35], v[52:53], v[34:35]
	v_cvt_pk_bf16_f32 v30, v30, v31
	v_cvt_pk_bf16_f32 v31, v32, v33
	v_cvt_pk_bf16_f32 v32, v34, v35
	v_cvt_pk_bf16_f32 v33, v36, v37
	global_store_dwordx4 v[40:41], v[30:33], off nt
	global_load_dwordx4 v[30:33], v[42:43], off nt
	v_lshl_add_u64 v[34:35], s[4:5], 0, v[38:39]
	global_load_dwordx4 v[34:37], v[34:35], off nt
	v_pk_mul_f32 v[44:45], v[22:23], v[64:65]
	v_pk_mul_f32 v[50:51], v[24:25], v[66:67]
	v_pk_mul_f32 v[52:53], v[18:19], v[68:69]
	v_pk_mul_f32 v[54:55], v[20:21], v[70:71]
	v_or_b32_e32 v40, 8, v28
	v_pk_fma_f32 v[50:51], v[16:17], v[58:59], v[50:51]
	v_pk_fma_f32 v[44:45], v[14:15], v[56:57], v[44:45]
	v_pk_fma_f32 v[54:55], v[12:13], v[62:63], v[54:55]
	v_pk_fma_f32 v[52:53], v[10:11], v[60:61], v[52:53]
	v_ashrrev_i32_e32 v41, 31, v40
	v_lshlrev_b64 v[40:41], 11, v[40:41]
	v_or_b32_e32 v40, v40, v26
	v_lshl_add_u64 v[38:39], s[6:7], 0, v[38:39]
	v_lshl_add_u64 v[42:43], s[34:35], 0, v[40:41]
	s_waitcnt vmcnt(1)
	v_lshlrev_b32_e32 v56, 16, v30
	v_and_b32_e32 v57, 0xffff0000, v30
	v_lshlrev_b32_e32 v58, 16, v31
	v_and_b32_e32 v59, 0xffff0000, v31
	v_lshlrev_b32_e32 v60, 16, v32
	v_and_b32_e32 v61, 0xffff0000, v32
	v_lshlrev_b32_e32 v62, 16, v33
	v_and_b32_e32 v63, 0xffff0000, v33
	s_waitcnt vmcnt(0)
	v_lshlrev_b32_e32 v30, 16, v34
	v_and_b32_e32 v31, 0xffff0000, v34
	v_lshlrev_b32_e32 v32, 16, v35
	v_and_b32_e32 v33, 0xffff0000, v35
	v_lshlrev_b32_e32 v34, 16, v36
	v_and_b32_e32 v35, 0xffff0000, v36
	v_lshlrev_b32_e32 v36, 16, v37
	v_and_b32_e32 v37, 0xffff0000, v37
	v_pk_fma_f32 v[44:45], v[6:7], v[56:57], v[44:45]
	v_pk_fma_f32 v[50:51], v[8:9], v[58:59], v[50:51]
	v_pk_fma_f32 v[52:53], v[2:3], v[60:61], v[52:53]
	v_pk_fma_f32 v[54:55], v[4:5], v[62:63], v[54:55]
	v_pk_mul_f32 v[32:33], v[50:51], v[32:33]
	v_pk_mul_f32 v[30:31], v[44:45], v[30:31]
	v_pk_mul_f32 v[36:37], v[54:55], v[36:37]
	v_pk_mul_f32 v[34:35], v[52:53], v[34:35]
	v_cvt_pk_bf16_f32 v30, v30, v31
	v_cvt_pk_bf16_f32 v31, v32, v33
	v_cvt_pk_bf16_f32 v32, v34, v35
	v_cvt_pk_bf16_f32 v33, v36, v37
	global_store_dwordx4 v[38:39], v[30:33], off nt
	global_load_dwordx4 v[30:33], v[42:43], off nt
	v_lshl_add_u64 v[34:35], s[4:5], 0, v[40:41]
	global_load_dwordx4 v[34:37], v[34:35], off nt
	v_pk_mul_f32 v[44:45], v[22:23], v[56:57]
	v_pk_mul_f32 v[50:51], v[24:25], v[58:59]
	v_pk_mul_f32 v[52:53], v[18:19], v[60:61]
	v_pk_mul_f32 v[54:55], v[20:21], v[62:63]
	v_or_b32_e32 v38, 9, v28
	v_pk_fma_f32 v[50:51], v[16:17], v[66:67], v[50:51]
	v_pk_fma_f32 v[44:45], v[14:15], v[64:65], v[44:45]
	v_pk_fma_f32 v[54:55], v[12:13], v[70:71], v[54:55]
	v_pk_fma_f32 v[52:53], v[10:11], v[68:69], v[52:53]
	v_ashrrev_i32_e32 v39, 31, v38
	v_lshlrev_b64 v[38:39], 11, v[38:39]
	v_or_b32_e32 v38, v38, v26
	v_lshl_add_u64 v[40:41], s[6:7], 0, v[40:41]
	v_lshl_add_u64 v[42:43], s[34:35], 0, v[38:39]
	s_waitcnt vmcnt(1)
	v_lshlrev_b32_e32 v64, 16, v30
	v_and_b32_e32 v65, 0xffff0000, v30
	v_lshlrev_b32_e32 v66, 16, v31
	v_and_b32_e32 v67, 0xffff0000, v31
	v_lshlrev_b32_e32 v68, 16, v32
	v_and_b32_e32 v69, 0xffff0000, v32
	v_lshlrev_b32_e32 v70, 16, v33
	v_and_b32_e32 v71, 0xffff0000, v33
	s_waitcnt vmcnt(0)
	v_lshlrev_b32_e32 v30, 16, v34
	v_and_b32_e32 v31, 0xffff0000, v34
	v_lshlrev_b32_e32 v32, 16, v35
	v_and_b32_e32 v33, 0xffff0000, v35
	v_lshlrev_b32_e32 v34, 16, v36
	v_and_b32_e32 v35, 0xffff0000, v36
	v_lshlrev_b32_e32 v36, 16, v37
	v_and_b32_e32 v37, 0xffff0000, v37
	v_pk_fma_f32 v[44:45], v[6:7], v[64:65], v[44:45]
	v_pk_fma_f32 v[50:51], v[8:9], v[66:67], v[50:51]
	v_pk_fma_f32 v[52:53], v[2:3], v[68:69], v[52:53]
	v_pk_fma_f32 v[54:55], v[4:5], v[70:71], v[54:55]
	v_pk_mul_f32 v[32:33], v[50:51], v[32:33]
	v_pk_mul_f32 v[30:31], v[44:45], v[30:31]
	v_pk_mul_f32 v[36:37], v[54:55], v[36:37]
	v_pk_mul_f32 v[34:35], v[52:53], v[34:35]
	v_cvt_pk_bf16_f32 v30, v30, v31
	v_cvt_pk_bf16_f32 v31, v32, v33
	v_cvt_pk_bf16_f32 v32, v34, v35
	v_cvt_pk_bf16_f32 v33, v36, v37
	global_store_dwordx4 v[40:41], v[30:33], off nt
	global_load_dwordx4 v[30:33], v[42:43], off nt
	v_lshl_add_u64 v[34:35], s[4:5], 0, v[38:39]
	global_load_dwordx4 v[34:37], v[34:35], off nt
	v_pk_mul_f32 v[44:45], v[22:23], v[64:65]
	v_pk_mul_f32 v[50:51], v[24:25], v[66:67]
	v_pk_mul_f32 v[52:53], v[18:19], v[68:69]
	v_pk_mul_f32 v[54:55], v[20:21], v[70:71]
	v_or_b32_e32 v40, 10, v28
	v_pk_fma_f32 v[50:51], v[16:17], v[58:59], v[50:51]
	v_pk_fma_f32 v[44:45], v[14:15], v[56:57], v[44:45]
	v_pk_fma_f32 v[54:55], v[12:13], v[62:63], v[54:55]
	v_pk_fma_f32 v[52:53], v[10:11], v[60:61], v[52:53]
	v_ashrrev_i32_e32 v41, 31, v40
	v_lshlrev_b64 v[40:41], 11, v[40:41]
	v_or_b32_e32 v40, v40, v26
	v_lshl_add_u64 v[38:39], s[6:7], 0, v[38:39]
	v_lshl_add_u64 v[42:43], s[34:35], 0, v[40:41]
	s_waitcnt vmcnt(1)
	v_lshlrev_b32_e32 v56, 16, v30
	v_and_b32_e32 v57, 0xffff0000, v30
	v_lshlrev_b32_e32 v58, 16, v31
	v_and_b32_e32 v59, 0xffff0000, v31
	v_lshlrev_b32_e32 v60, 16, v32
	v_and_b32_e32 v61, 0xffff0000, v32
	v_lshlrev_b32_e32 v62, 16, v33
	v_and_b32_e32 v63, 0xffff0000, v33
	s_waitcnt vmcnt(0)
	v_lshlrev_b32_e32 v30, 16, v34
	v_and_b32_e32 v31, 0xffff0000, v34
	v_lshlrev_b32_e32 v32, 16, v35
	v_and_b32_e32 v33, 0xffff0000, v35
	v_lshlrev_b32_e32 v34, 16, v36
	v_and_b32_e32 v35, 0xffff0000, v36
	v_lshlrev_b32_e32 v36, 16, v37
	v_and_b32_e32 v37, 0xffff0000, v37
	v_pk_fma_f32 v[44:45], v[6:7], v[56:57], v[44:45]
	v_pk_fma_f32 v[50:51], v[8:9], v[58:59], v[50:51]
	v_pk_fma_f32 v[52:53], v[2:3], v[60:61], v[52:53]
	v_pk_fma_f32 v[54:55], v[4:5], v[62:63], v[54:55]
	v_pk_mul_f32 v[32:33], v[50:51], v[32:33]
	v_pk_mul_f32 v[30:31], v[44:45], v[30:31]
	v_pk_mul_f32 v[36:37], v[54:55], v[36:37]
	v_pk_mul_f32 v[34:35], v[52:53], v[34:35]
	v_cvt_pk_bf16_f32 v30, v30, v31
	v_cvt_pk_bf16_f32 v31, v32, v33
	v_cvt_pk_bf16_f32 v32, v34, v35
	v_cvt_pk_bf16_f32 v33, v36, v37
	global_store_dwordx4 v[38:39], v[30:33], off nt
	global_load_dwordx4 v[30:33], v[42:43], off nt
	v_lshl_add_u64 v[34:35], s[4:5], 0, v[40:41]
	global_load_dwordx4 v[34:37], v[34:35], off nt
	v_pk_mul_f32 v[44:45], v[22:23], v[56:57]
	v_pk_mul_f32 v[50:51], v[24:25], v[58:59]
	v_pk_mul_f32 v[52:53], v[18:19], v[60:61]
	v_pk_mul_f32 v[54:55], v[20:21], v[62:63]
	v_or_b32_e32 v38, 11, v28
	v_pk_fma_f32 v[50:51], v[16:17], v[66:67], v[50:51]
	v_pk_fma_f32 v[44:45], v[14:15], v[64:65], v[44:45]
	v_pk_fma_f32 v[54:55], v[12:13], v[70:71], v[54:55]
	v_pk_fma_f32 v[52:53], v[10:11], v[68:69], v[52:53]
	v_ashrrev_i32_e32 v39, 31, v38
	v_lshlrev_b64 v[38:39], 11, v[38:39]
	v_or_b32_e32 v38, v38, v26
	v_lshl_add_u64 v[40:41], s[6:7], 0, v[40:41]
	v_lshl_add_u64 v[42:43], s[34:35], 0, v[38:39]
	s_waitcnt vmcnt(1)
	v_lshlrev_b32_e32 v64, 16, v30
	v_and_b32_e32 v65, 0xffff0000, v30
	v_lshlrev_b32_e32 v66, 16, v31
	v_and_b32_e32 v67, 0xffff0000, v31
	v_lshlrev_b32_e32 v68, 16, v32
	v_and_b32_e32 v69, 0xffff0000, v32
	v_lshlrev_b32_e32 v70, 16, v33
	v_and_b32_e32 v71, 0xffff0000, v33
	s_waitcnt vmcnt(0)
	v_lshlrev_b32_e32 v30, 16, v34
	v_and_b32_e32 v31, 0xffff0000, v34
	v_lshlrev_b32_e32 v32, 16, v35
	v_and_b32_e32 v33, 0xffff0000, v35
	v_lshlrev_b32_e32 v34, 16, v36
	v_and_b32_e32 v35, 0xffff0000, v36
	v_lshlrev_b32_e32 v36, 16, v37
	v_and_b32_e32 v37, 0xffff0000, v37
	v_pk_fma_f32 v[44:45], v[6:7], v[64:65], v[44:45]
	v_pk_fma_f32 v[50:51], v[8:9], v[66:67], v[50:51]
	v_pk_fma_f32 v[52:53], v[2:3], v[68:69], v[52:53]
	v_pk_fma_f32 v[54:55], v[4:5], v[70:71], v[54:55]
	v_pk_mul_f32 v[32:33], v[50:51], v[32:33]
	v_pk_mul_f32 v[30:31], v[44:45], v[30:31]
	v_pk_mul_f32 v[36:37], v[54:55], v[36:37]
	v_pk_mul_f32 v[34:35], v[52:53], v[34:35]
	v_cvt_pk_bf16_f32 v30, v30, v31
	v_cvt_pk_bf16_f32 v31, v32, v33
	v_cvt_pk_bf16_f32 v32, v34, v35
	v_cvt_pk_bf16_f32 v33, v36, v37
	global_store_dwordx4 v[40:41], v[30:33], off nt
	global_load_dwordx4 v[30:33], v[42:43], off nt
	v_lshl_add_u64 v[34:35], s[4:5], 0, v[38:39]
	global_load_dwordx4 v[34:37], v[34:35], off nt
	v_pk_mul_f32 v[44:45], v[22:23], v[64:65]
	v_pk_mul_f32 v[50:51], v[24:25], v[66:67]
	v_pk_mul_f32 v[52:53], v[18:19], v[68:69]
	v_pk_mul_f32 v[54:55], v[20:21], v[70:71]
	v_or_b32_e32 v40, 12, v28
	v_pk_fma_f32 v[50:51], v[16:17], v[58:59], v[50:51]
	v_pk_fma_f32 v[44:45], v[14:15], v[56:57], v[44:45]
	v_pk_fma_f32 v[54:55], v[12:13], v[62:63], v[54:55]
	v_pk_fma_f32 v[52:53], v[10:11], v[60:61], v[52:53]
	v_ashrrev_i32_e32 v41, 31, v40
	v_lshlrev_b64 v[40:41], 11, v[40:41]
	v_or_b32_e32 v40, v40, v26
	v_lshl_add_u64 v[38:39], s[6:7], 0, v[38:39]
	v_lshl_add_u64 v[42:43], s[34:35], 0, v[40:41]
	s_waitcnt vmcnt(1)
	v_lshlrev_b32_e32 v56, 16, v30
	v_and_b32_e32 v57, 0xffff0000, v30
	v_lshlrev_b32_e32 v58, 16, v31
	v_and_b32_e32 v59, 0xffff0000, v31
	v_lshlrev_b32_e32 v60, 16, v32
	v_and_b32_e32 v61, 0xffff0000, v32
	v_lshlrev_b32_e32 v62, 16, v33
	v_and_b32_e32 v63, 0xffff0000, v33
	s_waitcnt vmcnt(0)
	v_lshlrev_b32_e32 v30, 16, v34
	v_and_b32_e32 v31, 0xffff0000, v34
	v_lshlrev_b32_e32 v32, 16, v35
	v_and_b32_e32 v33, 0xffff0000, v35
	v_lshlrev_b32_e32 v34, 16, v36
	v_and_b32_e32 v35, 0xffff0000, v36
	v_lshlrev_b32_e32 v36, 16, v37
	v_and_b32_e32 v37, 0xffff0000, v37
	v_pk_fma_f32 v[44:45], v[6:7], v[56:57], v[44:45]
	v_pk_fma_f32 v[50:51], v[8:9], v[58:59], v[50:51]
	v_pk_fma_f32 v[52:53], v[2:3], v[60:61], v[52:53]
	v_pk_fma_f32 v[54:55], v[4:5], v[62:63], v[54:55]
	v_pk_mul_f32 v[32:33], v[50:51], v[32:33]
	v_pk_mul_f32 v[30:31], v[44:45], v[30:31]
	v_pk_mul_f32 v[36:37], v[54:55], v[36:37]
	v_pk_mul_f32 v[34:35], v[52:53], v[34:35]
	v_cvt_pk_bf16_f32 v30, v30, v31
	v_cvt_pk_bf16_f32 v31, v32, v33
	v_cvt_pk_bf16_f32 v32, v34, v35
	v_cvt_pk_bf16_f32 v33, v36, v37
	global_store_dwordx4 v[38:39], v[30:33], off nt
	global_load_dwordx4 v[30:33], v[42:43], off nt
	v_lshl_add_u64 v[34:35], s[4:5], 0, v[40:41]
	global_load_dwordx4 v[34:37], v[34:35], off nt
	v_pk_mul_f32 v[44:45], v[22:23], v[56:57]
	v_pk_mul_f32 v[50:51], v[24:25], v[58:59]
	v_pk_mul_f32 v[52:53], v[18:19], v[60:61]
	v_pk_mul_f32 v[54:55], v[20:21], v[62:63]
	v_or_b32_e32 v38, 13, v28
	v_pk_fma_f32 v[50:51], v[16:17], v[66:67], v[50:51]
	v_pk_fma_f32 v[44:45], v[14:15], v[64:65], v[44:45]
	v_pk_fma_f32 v[54:55], v[12:13], v[70:71], v[54:55]
	v_pk_fma_f32 v[52:53], v[10:11], v[68:69], v[52:53]
	v_ashrrev_i32_e32 v39, 31, v38
	v_lshlrev_b64 v[38:39], 11, v[38:39]
	v_or_b32_e32 v38, v38, v26
	v_lshl_add_u64 v[40:41], s[6:7], 0, v[40:41]
	v_lshl_add_u64 v[42:43], s[34:35], 0, v[38:39]
	v_or_b32_e32 v28, 14, v28
	v_ashrrev_i32_e32 v29, 31, v28
	s_waitcnt vmcnt(1)
	v_lshlrev_b32_e32 v64, 16, v30
	v_and_b32_e32 v65, 0xffff0000, v30
	v_lshlrev_b32_e32 v66, 16, v31
	v_and_b32_e32 v67, 0xffff0000, v31
	v_lshlrev_b32_e32 v68, 16, v32
	v_and_b32_e32 v69, 0xffff0000, v32
	v_lshlrev_b32_e32 v70, 16, v33
	v_and_b32_e32 v71, 0xffff0000, v33
	s_waitcnt vmcnt(0)
	v_lshlrev_b32_e32 v30, 16, v34
	v_and_b32_e32 v31, 0xffff0000, v34
	v_lshlrev_b32_e32 v32, 16, v35
	v_and_b32_e32 v33, 0xffff0000, v35
	v_lshlrev_b32_e32 v34, 16, v36
	v_and_b32_e32 v35, 0xffff0000, v36
	v_lshlrev_b32_e32 v36, 16, v37
	v_and_b32_e32 v37, 0xffff0000, v37
	v_pk_fma_f32 v[44:45], v[6:7], v[64:65], v[44:45]
	v_pk_fma_f32 v[50:51], v[8:9], v[66:67], v[50:51]
	v_pk_fma_f32 v[52:53], v[2:3], v[68:69], v[52:53]
	v_pk_fma_f32 v[54:55], v[4:5], v[70:71], v[54:55]
	v_pk_mul_f32 v[32:33], v[50:51], v[32:33]
	v_pk_mul_f32 v[30:31], v[44:45], v[30:31]
	v_pk_mul_f32 v[36:37], v[54:55], v[36:37]
	v_pk_mul_f32 v[34:35], v[52:53], v[34:35]
	v_cvt_pk_bf16_f32 v30, v30, v31
	v_cvt_pk_bf16_f32 v31, v32, v33
	v_cvt_pk_bf16_f32 v32, v34, v35
	v_cvt_pk_bf16_f32 v33, v36, v37
	global_store_dwordx4 v[40:41], v[30:33], off nt
	global_load_dwordx4 v[30:33], v[42:43], off nt
	v_lshl_add_u64 v[34:35], s[4:5], 0, v[38:39]
	global_load_dwordx4 v[34:37], v[34:35], off nt
	v_lshlrev_b64 v[40:41], 11, v[28:29]
	v_pk_mul_f32 v[28:29], v[22:23], v[64:65]
	v_pk_mul_f32 v[44:45], v[24:25], v[66:67]
	v_pk_mul_f32 v[50:51], v[18:19], v[68:69]
	v_pk_mul_f32 v[52:53], v[20:21], v[70:71]
	v_pk_fma_f32 v[44:45], v[16:17], v[58:59], v[44:45]
	v_pk_fma_f32 v[28:29], v[14:15], v[56:57], v[28:29]
	v_pk_fma_f32 v[52:53], v[12:13], v[62:63], v[52:53]
	v_pk_fma_f32 v[50:51], v[10:11], v[60:61], v[50:51]
	v_or_b32_e32 v40, v40, v26
	v_lshl_add_u64 v[38:39], s[6:7], 0, v[38:39]
	v_lshl_add_u64 v[42:43], s[34:35], 0, v[40:41]
	s_waitcnt vmcnt(1)
	v_lshlrev_b32_e32 v54, 16, v30
	v_and_b32_e32 v55, 0xffff0000, v30
	v_lshlrev_b32_e32 v56, 16, v31
	v_and_b32_e32 v57, 0xffff0000, v31
	v_lshlrev_b32_e32 v58, 16, v32
	v_and_b32_e32 v59, 0xffff0000, v32
	v_lshlrev_b32_e32 v60, 16, v33
	v_and_b32_e32 v61, 0xffff0000, v33
	s_waitcnt vmcnt(0)
	v_lshlrev_b32_e32 v30, 16, v34
	v_and_b32_e32 v31, 0xffff0000, v34
	v_lshlrev_b32_e32 v32, 16, v35
	v_and_b32_e32 v33, 0xffff0000, v35
	v_lshlrev_b32_e32 v34, 16, v36
	v_and_b32_e32 v35, 0xffff0000, v36
	v_lshlrev_b32_e32 v36, 16, v37
	v_and_b32_e32 v37, 0xffff0000, v37
	v_pk_fma_f32 v[28:29], v[6:7], v[54:55], v[28:29]
	v_pk_fma_f32 v[44:45], v[8:9], v[56:57], v[44:45]
	v_pk_fma_f32 v[50:51], v[2:3], v[58:59], v[50:51]
	v_pk_fma_f32 v[52:53], v[4:5], v[60:61], v[52:53]
	v_pk_mul_f32 v[32:33], v[44:45], v[32:33]
	v_pk_mul_f32 v[28:29], v[28:29], v[30:31]
	v_pk_mul_f32 v[36:37], v[52:53], v[36:37]
	v_pk_mul_f32 v[30:31], v[50:51], v[34:35]
	v_cvt_pk_bf16_f32 v28, v28, v29
	v_cvt_pk_bf16_f32 v29, v32, v33
	v_cvt_pk_bf16_f32 v30, v30, v31
	v_cvt_pk_bf16_f32 v31, v36, v37
	global_store_dwordx4 v[38:39], v[28:31], off nt
	global_load_dwordx4 v[28:31], v[42:43], off nt
	v_lshl_add_u64 v[32:33], s[4:5], 0, v[40:41]
	global_load_dwordx4 v[32:35], v[32:33], off nt
	v_or_b32_e32 v36, 15, v48
	v_pk_mul_f32 v[42:43], v[22:23], v[54:55]
	v_pk_mul_f32 v[44:45], v[24:25], v[56:57]
	v_pk_mul_f32 v[48:49], v[18:19], v[58:59]
	v_pk_mul_f32 v[50:51], v[20:21], v[60:61]
	v_pk_fma_f32 v[44:45], v[16:17], v[66:67], v[44:45]
	v_pk_fma_f32 v[42:43], v[14:15], v[64:65], v[42:43]
	v_pk_fma_f32 v[50:51], v[12:13], v[70:71], v[50:51]
	v_pk_fma_f32 v[48:49], v[10:11], v[68:69], v[48:49]
	v_ashrrev_i32_e32 v37, 31, v36
	v_lshlrev_b64 v[36:37], 11, v[36:37]
	v_or_b32_e32 v36, v36, v26
	v_lshl_add_u64 v[38:39], s[6:7], 0, v[40:41]
	v_lshl_add_u64 v[40:41], s[34:35], 0, v[36:37]
	s_waitcnt vmcnt(1)
	v_lshlrev_b32_e32 v52, 16, v28
	v_and_b32_e32 v53, 0xffff0000, v28
	v_lshlrev_b32_e32 v62, 16, v29
	v_and_b32_e32 v63, 0xffff0000, v29
	v_lshlrev_b32_e32 v64, 16, v30
	v_and_b32_e32 v65, 0xffff0000, v30
	v_lshlrev_b32_e32 v66, 16, v31
	v_and_b32_e32 v67, 0xffff0000, v31
	s_waitcnt vmcnt(0)
	v_lshlrev_b32_e32 v28, 16, v32
	v_and_b32_e32 v29, 0xffff0000, v32
	v_lshlrev_b32_e32 v30, 16, v33
	v_and_b32_e32 v31, 0xffff0000, v33
	v_lshlrev_b32_e32 v32, 16, v34
	v_and_b32_e32 v33, 0xffff0000, v34
	v_lshlrev_b32_e32 v34, 16, v35
	v_and_b32_e32 v35, 0xffff0000, v35
	v_pk_fma_f32 v[42:43], v[6:7], v[52:53], v[42:43]
	v_pk_fma_f32 v[44:45], v[8:9], v[62:63], v[44:45]
	v_pk_fma_f32 v[48:49], v[2:3], v[64:65], v[48:49]
	v_pk_fma_f32 v[50:51], v[4:5], v[66:67], v[50:51]
	v_pk_mul_f32 v[30:31], v[44:45], v[30:31]
	v_pk_mul_f32 v[28:29], v[42:43], v[28:29]
	v_pk_mul_f32 v[34:35], v[50:51], v[34:35]
	v_pk_mul_f32 v[32:33], v[48:49], v[32:33]
	v_cvt_pk_bf16_f32 v28, v28, v29
	v_cvt_pk_bf16_f32 v29, v30, v31
	v_cvt_pk_bf16_f32 v30, v32, v33
	v_cvt_pk_bf16_f32 v31, v34, v35
	global_store_dwordx4 v[38:39], v[28:31], off nt
	global_load_dwordx4 v[28:31], v[40:41], off nt
	v_lshl_add_u64 v[32:33], s[4:5], 0, v[36:37]
	global_load_dwordx4 v[32:35], v[32:33], off nt
	v_pk_mul_f32 v[22:23], v[22:23], v[52:53]
	v_pk_mul_f32 v[24:25], v[24:25], v[62:63]
	v_pk_mul_f32 v[18:19], v[18:19], v[64:65]
	v_pk_mul_f32 v[20:21], v[20:21], v[66:67]
	v_pk_fma_f32 v[16:17], v[16:17], v[56:57], v[24:25]
	v_pk_fma_f32 v[14:15], v[14:15], v[54:55], v[22:23]
	v_pk_fma_f32 v[12:13], v[12:13], v[60:61], v[20:21]
	v_pk_fma_f32 v[10:11], v[10:11], v[58:59], v[18:19]
	v_lshl_add_u64 v[36:37], s[6:7], 0, v[36:37]
	s_waitcnt vmcnt(1)
	v_lshlrev_b32_e32 v18, 16, v28
	v_and_b32_e32 v19, 0xffff0000, v28
	v_lshlrev_b32_e32 v20, 16, v29
	v_and_b32_e32 v21, 0xffff0000, v29
	v_lshlrev_b32_e32 v22, 16, v30
	v_and_b32_e32 v23, 0xffff0000, v30
	v_lshlrev_b32_e32 v24, 16, v31
	v_and_b32_e32 v25, 0xffff0000, v31
	s_waitcnt vmcnt(0)
	v_lshlrev_b32_e32 v28, 16, v32
	v_and_b32_e32 v29, 0xffff0000, v32
	v_lshlrev_b32_e32 v30, 16, v33
	v_and_b32_e32 v31, 0xffff0000, v33
	v_lshlrev_b32_e32 v32, 16, v34
	v_and_b32_e32 v33, 0xffff0000, v34
	v_lshlrev_b32_e32 v34, 16, v35
	v_and_b32_e32 v35, 0xffff0000, v35
	v_pk_fma_f32 v[6:7], v[6:7], v[18:19], v[14:15]
	v_pk_fma_f32 v[8:9], v[8:9], v[20:21], v[16:17]
	v_pk_fma_f32 v[2:3], v[2:3], v[22:23], v[10:11]
	v_pk_fma_f32 v[4:5], v[4:5], v[24:25], v[12:13]
	v_pk_mul_f32 v[8:9], v[8:9], v[30:31]
	v_pk_mul_f32 v[6:7], v[6:7], v[28:29]
	v_pk_mul_f32 v[10:11], v[4:5], v[34:35]
	v_pk_mul_f32 v[4:5], v[2:3], v[32:33]
	v_cvt_pk_bf16_f32 v2, v6, v7
	v_cvt_pk_bf16_f32 v3, v8, v9
	v_cvt_pk_bf16_f32 v4, v4, v5
	v_cvt_pk_bf16_f32 v5, v10, v11
	global_store_dwordx4 v[36:37], v[2:5], off nt
	s_andn2_b64 exec, exec, s[12:13]
	s_cbranch_execz .LBB0_275

.LBB0_278:
	s_cmpk_lt_i32 s25, 0x200
	s_movk_i32 s4, 0x540
	s_cselect_b32 s26, s4, 0xf0
	s_add_i32 s26, s26, s25
	s_cmpk_gt_i32 s26, 0x7f
	s_mov_b64 s[4:5], -1
	s_cbranch_scc0 .LBB0_293
	s_cmpk_gt_u32 s26, 0x33f
	s_cbranch_scc0 .LBB0_285
	s_cmpk_gt_u32 s26, 0x53f
	s_cbranch_scc0 .LBB0_282
	s_add_i32 s50, s26, 0xfffffac0
	s_lshl_b64 s[4:5], s[50:51], 13
	v_readlane_b32 s80, v254, 5
	v_mov_b32_e32 v19, s5
	v_or_b32_e32 v18, s4, v70
	v_readlane_b32 s82, v254, 7
	v_readlane_b32 s83, v254, 8
	s_mov_b64 s[4:5], 0x4000
	v_readlane_b32 s81, v254, 6
	v_lshl_add_u64 v[10:11], v[18:19], 2, s[82:83]
	global_load_dwordx4 v[2:5], v[10:11], off offset:16 nt
	global_load_dwordx4 v[6:9], v[10:11], off nt
	v_lshl_add_u64 v[14:15], v[10:11], 0, s[4:5]
	v_add_co_u32_e32 v10, vcc, 0x4000, v10
	v_lshl_add_u64 v[18:19], v[18:19], 1, s[10:11]
	s_nop 0
	v_addc_co_u32_e32 v11, vcc, 0, v11, vcc
	global_load_dwordx4 v[10:13], v[10:11], off nt
	s_nop 0
	global_load_dwordx4 v[14:17], v[14:15], off offset:16 nt
	v_readlane_b32 s84, v254, 9
	v_readlane_b32 s85, v254, 10
	v_readlane_b32 s86, v254, 11
	v_readlane_b32 s87, v254, 12
	v_readlane_b32 s88, v254, 13
	v_readlane_b32 s89, v254, 14
	v_readlane_b32 s90, v254, 15
	v_readlane_b32 s91, v254, 16
	v_readlane_b32 s92, v254, 17
	v_readlane_b32 s93, v254, 18
	v_readlane_b32 s94, v254, 19
	v_readlane_b32 s95, v254, 20
	s_mov_b64 s[4:5], 0
	s_waitcnt vmcnt(0)
	v_cvt_pk_bf16_f32 v6, v6, v7
	v_cvt_pk_bf16_f32 v7, v8, v9
	v_cvt_pk_bf16_f32 v8, v2, v3
	v_cvt_pk_bf16_f32 v9, v4, v5
	global_store_dwordx4 v[18:19], v[6:9], off
	v_cvt_pk_bf16_f32 v2, v10, v11
	s_nop 0
	v_add_co_u32_e32 v6, vcc, 0x2000, v18
	v_cvt_pk_bf16_f32 v3, v12, v13
	v_cvt_pk_bf16_f32 v4, v14, v15
	v_cvt_pk_bf16_f32 v5, v16, v17
	v_addc_co_u32_e32 v7, vcc, 0, v19, vcc
	global_store_dwordx4 v[6:7], v[2:5], off
.LBB0_282:
	s_andn2_b64 vcc, exec, s[4:5]
	s_cbranch_vccnz .LBB0_284
	v_lshl_add_u32 v72, s26, 5, v71
	v_lshlrev_b64 v[2:3], 12, v[72:73]
	v_lshl_add_u64 v[2:3], v[74:75], 0, v[2:3]
	global_load_dwordx4 v[46:49], v[2:3], off nt
	global_load_dwordx4 v[30:33], v[2:3], off offset:1024 nt
	global_load_dwordx4 v[18:21], v[2:3], off offset:2048 nt
	global_load_dwordx4 v[14:17], v[2:3], off offset:3072 nt
	v_or_b32_e32 v86, 1, v72
	v_mov_b32_e32 v87, v73
	v_lshlrev_b64 v[2:3], 12, v[86:87]
	v_lshl_add_u64 v[2:3], v[74:75], 0, v[2:3]
	global_load_dwordx4 v[54:57], v[2:3], off nt
	global_load_dwordx4 v[34:37], v[2:3], off offset:1024 nt
	global_load_dwordx4 v[22:25], v[2:3], off offset:2048 nt
	global_load_dwordx4 v[10:13], v[2:3], off offset:3072 nt
	v_and_b32_e32 v66, 64, v123
	v_add_u32_e32 v94, 64, v66
	v_or_b32_e32 v88, 2, v72
	v_mov_b32_e32 v89, v73
	v_lshlrev_b64 v[2:3], 12, v[88:89]
	v_lshl_add_u64 v[2:3], v[74:75], 0, v[2:3]
	global_load_dwordx4 v[58:61], v[2:3], off nt
	global_load_dwordx4 v[42:45], v[2:3], off offset:1024 nt
	global_load_dwordx4 v[26:29], v[2:3], off offset:2048 nt
	s_nop 0
	global_load_dwordx4 v[2:5], v[2:3], off offset:3072 nt
	v_or_b32_e32 v90, 3, v72
	v_mov_b32_e32 v91, v73
	v_lshlrev_b64 v[6:7], 12, v[90:91]
	v_lshl_add_u64 v[6:7], v[74:75], 0, v[6:7]
	global_load_dwordx4 v[62:65], v[6:7], off nt
	global_load_dwordx4 v[50:53], v[6:7], off offset:1024 nt
	global_load_dwordx4 v[38:41], v[6:7], off offset:2048 nt
	s_nop 0
	global_load_dwordx4 v[6:9], v[6:7], off offset:3072 nt
	s_mov_b32 s4, 0x358637bd
	s_waitcnt vmcnt(0)
	v_pk_mul_f32 v[66:67], v[48:49], v[48:49]
	v_pk_mul_f32 v[68:69], v[46:47], v[46:47]
	v_mul_f32_e32 v83, v14, v14
	v_pk_mov_b32 v[128:129], v[68:69], v[66:67] op_sel:[1,0]
	v_mov_b32_e32 v69, v67
	v_pk_add_f32 v[66:67], v[128:129], v[68:69]
	v_pk_mul_f32 v[68:69], v[32:33], v[32:33]
	v_pk_mul_f32 v[128:129], v[30:31], v[30:31]
	v_mul_f32_e32 v85, v15, v15
	v_pk_mov_b32 v[130:131], v[128:129], v[68:69] op_sel:[1,0]
	v_mov_b32_e32 v129, v69
	v_pk_add_f32 v[68:69], v[130:131], v[128:129]
	v_pk_add_f32 v[66:67], v[66:67], v[66:67] op_sel:[0,1] op_sel_hi:[1,0]
	v_pk_add_f32 v[68:69], v[68:69], v[68:69] op_sel:[0,1] op_sel_hi:[1,0]
	v_mov_b32_e32 v67, v83
	v_mov_b32_e32 v69, v85
	v_pk_add_f32 v[66:67], v[66:67], v[68:69]
	v_mul_f32_e32 v68, v19, v19
	v_mul_f32_e32 v92, v16, v16
	v_pk_fma_f32 v[68:69], v[18:19], v[18:19], v[68:69] op_sel_hi:[1,1,0]
	v_mul_f32_e32 v96, v17, v17
	v_mov_b32_e32 v69, v92
	v_mul_f32_e32 v92, v21, v21
	v_pk_fma_f32 v[128:129], v[20:21], v[20:21], v[92:93] op_sel_hi:[1,1,0]
	v_xor_b32_e32 v83, 8, v123
	v_mov_b32_e32 v129, v96
	v_pk_add_f32 v[68:69], v[68:69], v[128:129]
	v_xor_b32_e32 v85, 4, v123
	v_pk_add_f32 v[66:67], v[66:67], v[68:69]
	v_xor_b32_e32 v68, 32, v123
	v_cmp_lt_i32_e32 vcc, v68, v94
	v_xor_b32_e32 v69, 16, v123
	v_xor_b32_e32 v92, 2, v123
	v_cndmask_b32_e32 v68, v123, v68, vcc
	v_cmp_lt_i32_e32 vcc, v69, v94
	v_pk_mul_f32 v[128:129], v[56:57], v[56:57]
	v_pk_mul_f32 v[130:131], v[54:55], v[54:55]
	v_cndmask_b32_e32 v69, v123, v69, vcc
	v_cmp_lt_i32_e32 vcc, v83, v94
	v_pk_mov_b32 v[132:133], v[130:131], v[128:129] op_sel:[1,0]
	v_mov_b32_e32 v131, v129
	v_cndmask_b32_e32 v83, v123, v83, vcc
	v_cmp_lt_i32_e32 vcc, v85, v94
	v_pk_add_f32 v[128:129], v[132:133], v[130:131]
	v_pk_mul_f32 v[130:131], v[36:37], v[36:37]
	v_cndmask_b32_e32 v85, v123, v85, vcc
	v_cmp_lt_i32_e32 vcc, v92, v94
	v_pk_mul_f32 v[132:133], v[34:35], v[34:35]
	v_pk_add_f32 v[128:129], v[128:129], v[128:129] op_sel:[0,1] op_sel_hi:[1,0]
	v_cndmask_b32_e32 v92, v123, v92, vcc
	v_lshlrev_b32_e32 v96, 2, v92
	v_xor_b32_e32 v92, 1, v123
	v_cmp_lt_i32_e32 vcc, v92, v94
	v_pk_mov_b32 v[134:135], v[132:133], v[130:131] op_sel:[1,0]
	v_mov_b32_e32 v133, v131
	v_cndmask_b32_e32 v92, v123, v92, vcc
	v_pk_add_f32 v[130:131], v[134:135], v[132:133]
	v_lshlrev_b32_e32 v98, 2, v92
	v_mul_f32_e32 v92, v10, v10
	v_mul_f32_e32 v94, v11, v11
	v_pk_add_f32 v[130:131], v[130:131], v[130:131] op_sel:[0,1] op_sel_hi:[1,0]
	v_mov_b32_e32 v129, v92
	v_mov_b32_e32 v131, v94
	v_mul_f32_e32 v92, v23, v23
	v_mul_f32_e32 v132, v12, v12
	v_pk_add_f32 v[128:129], v[128:129], v[130:131]
	v_pk_fma_f32 v[130:131], v[22:23], v[22:23], v[92:93] op_sel_hi:[1,1,0]
	v_mul_f32_e32 v92, v25, v25
	v_mul_f32_e32 v134, v13, v13
	v_mov_b32_e32 v131, v132
	v_pk_fma_f32 v[132:133], v[24:25], v[24:25], v[92:93] op_sel_hi:[1,1,0]
	v_lshlrev_b32_e32 v68, 2, v68
	v_mov_b32_e32 v133, v134
	v_pk_add_f32 v[130:131], v[130:131], v[132:133]
	v_lshlrev_b32_e32 v69, 2, v69
	v_pk_add_f32 v[128:129], v[128:129], v[130:131]
	v_mov_b32_e32 v131, v66
	v_mov_b32_e32 v130, v128
	v_mov_b32_e32 v66, v129
	v_pk_add_f32 v[66:67], v[130:131], v[66:67]
	ds_bpermute_b32 v129, v68, v67
	ds_bpermute_b32 v128, v68, v66
	v_lshlrev_b32_e32 v83, 2, v83
	v_lshlrev_b32_e32 v85, 2, v85
	v_pk_mul_f32 v[130:131], v[58:59], v[58:59]
	s_waitcnt lgkmcnt(0)
	v_pk_add_f32 v[66:67], v[66:67], v[128:129]
	ds_bpermute_b32 v129, v69, v67
	ds_bpermute_b32 v128, v69, v66
	s_waitcnt lgkmcnt(0)
	v_pk_add_f32 v[66:67], v[66:67], v[128:129]
	ds_bpermute_b32 v129, v83, v67
	ds_bpermute_b32 v128, v83, v66
	s_waitcnt lgkmcnt(0)
	v_pk_add_f32 v[66:67], v[66:67], v[128:129]
	ds_bpermute_b32 v129, v85, v67
	ds_bpermute_b32 v128, v85, v66
	s_waitcnt lgkmcnt(0)
	v_pk_add_f32 v[66:67], v[66:67], v[128:129]
	ds_bpermute_b32 v129, v96, v67
	ds_bpermute_b32 v128, v96, v66
	s_waitcnt lgkmcnt(0)
	v_pk_add_f32 v[66:67], v[66:67], v[128:129]
	ds_bpermute_b32 v129, v98, v67
	ds_bpermute_b32 v128, v98, v66
	s_waitcnt lgkmcnt(0)
	v_pk_add_f32 v[66:67], v[66:67], v[128:129]
	v_mov_b64_e32 v[128:129], s[4:5]
	v_pk_fma_f32 v[66:67], v[66:67], s[56:57], v[128:129] op_sel_hi:[1,0,0]
	s_nop 0
	v_mul_f32_e32 v92, 0x4b800000, v67
	v_cmp_gt_f32_e64 s[4:5], s57, v67
	v_cmp_gt_f32_e32 vcc, s57, v66
	s_nop 0
	v_cndmask_b32_e64 v67, v67, v92, s[4:5]
	v_rsq_f32_e32 v67, v67
	s_nop 0
	v_mul_f32_e32 v92, 0x45800000, v67
	v_cndmask_b32_e64 v94, v67, v92, s[4:5]
	v_mul_f32_e32 v67, 0x4b800000, v66
	v_cndmask_b32_e32 v66, v66, v67, vcc
	v_rsq_f32_e32 v66, v66
	v_pk_mul_f32 v[46:47], v[46:47], v[94:95] op_sel_hi:[1,0]
	v_pk_mul_f32 v[48:49], v[48:49], v[94:95] op_sel_hi:[1,0]
	v_pk_mul_f32 v[30:31], v[30:31], v[94:95] op_sel_hi:[1,0]
	v_mul_f32_e32 v67, 0x45800000, v66
	v_cndmask_b32_e32 v92, v66, v67, vcc
	v_pk_mul_f32 v[66:67], v[60:61], v[60:61]
	v_pk_mul_f32 v[32:33], v[32:33], v[94:95] op_sel_hi:[1,0]
	v_pk_mov_b32 v[132:133], v[130:131], v[66:67] op_sel:[1,0]
	v_mov_b32_e32 v131, v67
	v_pk_add_f32 v[66:67], v[132:133], v[130:131]
	v_pk_mul_f32 v[130:131], v[44:45], v[44:45]
	v_pk_mul_f32 v[132:133], v[42:43], v[42:43]
	v_pk_add_f32 v[66:67], v[66:67], v[66:67] op_sel:[0,1] op_sel_hi:[1,0]
	v_pk_mov_b32 v[134:135], v[132:133], v[130:131] op_sel:[1,0]
	v_mov_b32_e32 v133, v131
	v_pk_add_f32 v[130:131], v[134:135], v[132:133]
	v_mul_f32_e32 v132, v2, v2
	v_mul_f32_e32 v133, v3, v3
	v_pk_add_f32 v[130:131], v[130:131], v[130:131] op_sel:[0,1] op_sel_hi:[1,0]
	v_mov_b32_e32 v67, v132
	v_mov_b32_e32 v131, v133
	v_pk_add_f32 v[66:67], v[66:67], v[130:131]
	v_mul_f32_e32 v130, v27, v27
	v_mul_f32_e32 v132, v29, v29
	v_mul_f32_e32 v134, v4, v4
	v_mul_f32_e32 v135, v5, v5
	v_pk_fma_f32 v[130:131], v[26:27], v[26:27], v[130:131] op_sel_hi:[1,1,0]
	v_pk_fma_f32 v[132:133], v[28:29], v[28:29], v[132:133] op_sel_hi:[1,1,0]
	v_mov_b32_e32 v131, v134
	v_mov_b32_e32 v133, v135
	v_pk_add_f32 v[130:131], v[130:131], v[132:133]
	v_pk_mul_f32 v[132:133], v[62:63], v[62:63]
	v_pk_add_f32 v[66:67], v[66:67], v[130:131]
	v_pk_mul_f32 v[130:131], v[64:65], v[64:65]
	v_pk_mul_f32 v[18:19], v[18:19], v[94:95] op_sel_hi:[1,0]
	v_pk_mov_b32 v[134:135], v[132:133], v[130:131] op_sel:[1,0]
	v_mov_b32_e32 v133, v131
	v_pk_add_f32 v[130:131], v[134:135], v[132:133]
	v_pk_mul_f32 v[132:133], v[52:53], v[52:53]
	v_pk_mul_f32 v[134:135], v[50:51], v[50:51]
	v_pk_add_f32 v[130:131], v[130:131], v[130:131] op_sel:[0,1] op_sel_hi:[1,0]
	v_pk_mov_b32 v[136:137], v[134:135], v[132:133] op_sel:[1,0]
	v_mov_b32_e32 v135, v133
	v_pk_add_f32 v[132:133], v[136:137], v[134:135]
	v_mul_f32_e32 v134, v6, v6
	v_mul_f32_e32 v135, v7, v7
	v_pk_add_f32 v[132:133], v[132:133], v[132:133] op_sel:[0,1] op_sel_hi:[1,0]
	v_mov_b32_e32 v131, v134
	v_mov_b32_e32 v133, v135
	v_pk_add_f32 v[130:131], v[130:131], v[132:133]
	v_mul_f32_e32 v132, v39, v39
	v_mul_f32_e32 v134, v41, v41
	v_mul_f32_e32 v136, v8, v8
	v_mul_f32_e32 v137, v9, v9
	v_pk_fma_f32 v[132:133], v[38:39], v[38:39], v[132:133] op_sel_hi:[1,1,0]
	v_pk_fma_f32 v[134:135], v[40:41], v[40:41], v[134:135] op_sel_hi:[1,1,0]
	v_mov_b32_e32 v133, v136
	v_mov_b32_e32 v135, v137
	v_pk_add_f32 v[132:133], v[132:133], v[134:135]
	v_pk_mul_f32 v[20:21], v[20:21], v[94:95] op_sel_hi:[1,0]
	v_pk_add_f32 v[130:131], v[130:131], v[132:133]
	v_mov_b32_e32 v133, v66
	v_mov_b32_e32 v132, v130
	v_mov_b32_e32 v66, v131
	v_pk_add_f32 v[66:67], v[132:133], v[66:67]
	ds_bpermute_b32 v131, v68, v67
	ds_bpermute_b32 v130, v68, v66
	v_pk_mul_f32 v[14:15], v[14:15], v[94:95] op_sel_hi:[1,0]
	v_pk_mul_f32 v[16:17], v[16:17], v[94:95] op_sel_hi:[1,0]
	v_pk_mul_f32 v[10:11], v[10:11], v[92:93] op_sel_hi:[1,0]
	v_pk_mul_f32 v[12:13], v[12:13], v[92:93] op_sel_hi:[1,0]
	s_waitcnt lgkmcnt(0)
	v_pk_add_f32 v[66:67], v[66:67], v[130:131]
	ds_bpermute_b32 v131, v69, v67
	ds_bpermute_b32 v130, v69, v66
	s_waitcnt lgkmcnt(0)
	v_pk_add_f32 v[66:67], v[66:67], v[130:131]
	ds_bpermute_b32 v69, v83, v67
	ds_bpermute_b32 v68, v83, v66
	s_waitcnt lgkmcnt(0)
	v_pk_add_f32 v[66:67], v[66:67], v[68:69]
	ds_bpermute_b32 v69, v85, v67
	ds_bpermute_b32 v68, v85, v66
	s_waitcnt lgkmcnt(0)
	v_pk_add_f32 v[66:67], v[66:67], v[68:69]
	ds_bpermute_b32 v69, v96, v67
	ds_bpermute_b32 v68, v96, v66
	s_waitcnt lgkmcnt(0)
	v_pk_add_f32 v[66:67], v[66:67], v[68:69]
	ds_bpermute_b32 v69, v98, v67
	ds_bpermute_b32 v68, v98, v66
	s_waitcnt lgkmcnt(0)
	v_pk_add_f32 v[66:67], v[66:67], v[68:69]
	s_nop 0
	v_pk_fma_f32 v[66:67], v[66:67], s[56:57], v[128:129] op_sel_hi:[1,0,0]
	s_nop 0
	v_mul_f32_e32 v68, 0x4b800000, v67
	v_cmp_gt_f32_e64 s[4:5], s57, v67
	v_cmp_gt_f32_e32 vcc, s57, v66
	s_nop 0
	v_cndmask_b32_e64 v67, v67, v68, s[4:5]
	v_rsq_f32_e32 v67, v67
	s_nop 0
	v_mul_f32_e32 v68, 0x45800000, v67
	v_cndmask_b32_e64 v98, v67, v68, s[4:5]
	v_mul_f32_e32 v67, 0x4b800000, v66
	v_cndmask_b32_e32 v66, v66, v67, vcc
	v_rsq_f32_e32 v66, v66
	v_pk_mul_f32 v[2:3], v[2:3], v[98:99] op_sel_hi:[1,0]
	v_pk_mul_f32 v[4:5], v[4:5], v[98:99] op_sel_hi:[1,0]
	v_mul_f32_e32 v67, 0x45800000, v66
	v_cndmask_b32_e32 v96, v66, v67, vcc
	global_load_dwordx4 v[66:69], v[76:77], off nt
	s_waitcnt vmcnt(0)
	v_pk_mul_f32 v[48:49], v[48:49], v[68:69]
	v_pk_mul_f32 v[46:47], v[46:47], v[66:67]
	s_nop 0
	v_cvt_pk_bf16_f32 v46, v46, v47
	v_cvt_pk_bf16_f32 v47, v48, v49
	v_lshlrev_b64 v[48:49], 11, v[72:73]
	v_lshl_add_u64 v[128:129], v[80:81], 0, v[48:49]
	global_store_dwordx2 v[128:129], v[46:47], off
	v_pk_mul_f32 v[46:47], v[54:55], v[92:93] op_sel_hi:[1,0]
	v_pk_mul_f32 v[48:49], v[56:57], v[92:93] op_sel_hi:[1,0]
	v_pk_mul_f32 v[46:47], v[46:47], v[66:67]
	v_pk_mul_f32 v[48:49], v[48:49], v[68:69]
	v_cvt_pk_bf16_f32 v46, v46, v47
	v_cvt_pk_bf16_f32 v47, v48, v49
	v_lshlrev_b64 v[48:49], 11, v[86:87]
	v_lshl_add_u64 v[54:55], v[80:81], 0, v[48:49]
	global_store_dwordx2 v[54:55], v[46:47], off
	v_pk_mul_f32 v[46:47], v[58:59], v[98:99] op_sel_hi:[1,0]
	v_pk_mul_f32 v[48:49], v[60:61], v[98:99] op_sel_hi:[1,0]
	v_pk_mul_f32 v[46:47], v[66:67], v[46:47]
	v_pk_mul_f32 v[48:49], v[68:69], v[48:49]
	v_cvt_pk_bf16_f32 v46, v46, v47
	v_cvt_pk_bf16_f32 v47, v48, v49
	v_lshlrev_b64 v[48:49], 11, v[88:89]
	v_lshl_add_u64 v[56:57], v[80:81], 0, v[48:49]
	global_store_dwordx2 v[56:57], v[46:47], off
	v_pk_mul_f32 v[46:47], v[62:63], v[96:97] op_sel_hi:[1,0]
	v_pk_mul_f32 v[48:49], v[64:65], v[96:97] op_sel_hi:[1,0]
	v_pk_mul_f32 v[46:47], v[66:67], v[46:47]
	v_pk_mul_f32 v[48:49], v[68:69], v[48:49]
	v_cvt_pk_bf16_f32 v46, v46, v47
	v_cvt_pk_bf16_f32 v47, v48, v49
	v_lshlrev_b64 v[48:49], 11, v[90:91]
	v_lshl_add_u64 v[58:59], v[80:81], 0, v[48:49]
	global_store_dwordx2 v[58:59], v[46:47], off
	global_load_dwordx4 v[46:49], v[76:77], off offset:1024 nt
	s_waitcnt vmcnt(0)
	v_pk_mul_f32 v[32:33], v[32:33], v[48:49]
	v_pk_mul_f32 v[30:31], v[30:31], v[46:47]
	s_nop 0
	v_cvt_pk_bf16_f32 v30, v30, v31
	v_cvt_pk_bf16_f32 v31, v32, v33
	global_store_dwordx2 v[128:129], v[30:31], off offset:512
	v_pk_mul_f32 v[30:31], v[34:35], v[92:93] op_sel_hi:[1,0]
	v_pk_mul_f32 v[32:33], v[36:37], v[92:93] op_sel_hi:[1,0]
	v_pk_mul_f32 v[30:31], v[30:31], v[46:47]
	v_pk_mul_f32 v[32:33], v[32:33], v[48:49]
	v_cvt_pk_bf16_f32 v30, v30, v31
	v_cvt_pk_bf16_f32 v31, v32, v33
	global_store_dwordx2 v[54:55], v[30:31], off offset:512
	v_pk_mul_f32 v[30:31], v[42:43], v[98:99] op_sel_hi:[1,0]
	v_pk_mul_f32 v[32:33], v[44:45], v[98:99] op_sel_hi:[1,0]
	v_pk_mul_f32 v[30:31], v[46:47], v[30:31]
	v_pk_mul_f32 v[32:33], v[48:49], v[32:33]
	v_cvt_pk_bf16_f32 v30, v30, v31
	v_cvt_pk_bf16_f32 v31, v32, v33
	global_store_dwordx2 v[56:57], v[30:31], off offset:512
	v_pk_mul_f32 v[30:31], v[50:51], v[96:97] op_sel_hi:[1,0]
	v_pk_mul_f32 v[32:33], v[52:53], v[96:97] op_sel_hi:[1,0]
	v_pk_mul_f32 v[30:31], v[46:47], v[30:31]
	v_pk_mul_f32 v[32:33], v[48:49], v[32:33]
	v_cvt_pk_bf16_f32 v30, v30, v31
	v_cvt_pk_bf16_f32 v31, v32, v33
	global_store_dwordx2 v[58:59], v[30:31], off offset:512
	global_load_dwordx4 v[30:33], v[76:77], off offset:2048 nt
	s_waitcnt vmcnt(0)
	v_pk_mul_f32 v[20:21], v[20:21], v[32:33]
	v_pk_mul_f32 v[18:19], v[18:19], v[30:31]
	s_nop 0
	v_cvt_pk_bf16_f32 v18, v18, v19
	v_cvt_pk_bf16_f32 v19, v20, v21
	global_store_dwordx2 v[128:129], v[18:19], off offset:1024
	v_pk_mul_f32 v[18:19], v[22:23], v[92:93] op_sel_hi:[1,0]
	v_pk_mul_f32 v[20:21], v[24:25], v[92:93] op_sel_hi:[1,0]
	v_pk_mul_f32 v[18:19], v[18:19], v[30:31]
	v_pk_mul_f32 v[20:21], v[20:21], v[32:33]
	v_cvt_pk_bf16_f32 v18, v18, v19
	v_cvt_pk_bf16_f32 v19, v20, v21
	global_store_dwordx2 v[54:55], v[18:19], off offset:1024
	v_pk_mul_f32 v[18:19], v[26:27], v[98:99] op_sel_hi:[1,0]
	v_pk_mul_f32 v[20:21], v[28:29], v[98:99] op_sel_hi:[1,0]
	v_pk_mul_f32 v[18:19], v[18:19], v[30:31]
	v_pk_mul_f32 v[20:21], v[20:21], v[32:33]
	v_cvt_pk_bf16_f32 v18, v18, v19
	v_cvt_pk_bf16_f32 v19, v20, v21
	global_store_dwordx2 v[56:57], v[18:19], off offset:1024
	v_pk_mul_f32 v[18:19], v[38:39], v[96:97] op_sel_hi:[1,0]
	v_pk_mul_f32 v[20:21], v[40:41], v[96:97] op_sel_hi:[1,0]
	v_pk_mul_f32 v[18:19], v[30:31], v[18:19]
	v_pk_mul_f32 v[20:21], v[32:33], v[20:21]
	v_cvt_pk_bf16_f32 v18, v18, v19
	v_cvt_pk_bf16_f32 v19, v20, v21
	global_store_dwordx2 v[58:59], v[18:19], off offset:1024
	global_load_dwordx4 v[18:21], v[76:77], off offset:3072 nt
	s_waitcnt vmcnt(0)
	v_pk_mul_f32 v[4:5], v[4:5], v[20:21]
	v_pk_mul_f32 v[2:3], v[2:3], v[18:19]
	v_pk_mul_f32 v[16:17], v[16:17], v[20:21]
	v_cvt_pk_bf16_f32 v2, v2, v3
	v_cvt_pk_bf16_f32 v3, v4, v5
	global_store_dwordx2 v[56:57], v[2:3], off offset:1536
	v_pk_mul_f32 v[2:3], v[6:7], v[96:97] op_sel_hi:[1,0]
	v_pk_mul_f32 v[4:5], v[8:9], v[96:97] op_sel_hi:[1,0]
	v_pk_mul_f32 v[14:15], v[14:15], v[18:19]
	v_pk_mul_f32 v[12:13], v[12:13], v[20:21]
	v_pk_mul_f32 v[10:11], v[10:11], v[18:19]
	v_pk_mul_f32 v[4:5], v[4:5], v[20:21]
	v_pk_mul_f32 v[2:3], v[2:3], v[18:19]
	v_cvt_pk_bf16_f32 v14, v14, v15
	v_cvt_pk_bf16_f32 v15, v16, v17
	v_cvt_pk_bf16_f32 v10, v10, v11
	v_cvt_pk_bf16_f32 v11, v12, v13
	v_cvt_pk_bf16_f32 v2, v2, v3
	v_cvt_pk_bf16_f32 v3, v4, v5
	global_store_dwordx2 v[128:129], v[14:15], off offset:1536
	global_store_dwordx2 v[54:55], v[10:11], off offset:1536
	global_store_dwordx2 v[58:59], v[2:3], off offset:1536

.LBB0_326:
	global_load_dword v4, v[2:3], off nt
	v_lshl_add_u64 v[2:3], v[2:3], 0, s[50:51]
	global_load_dword v5, v[2:3], off nt
	v_lshl_add_u64 v[2:3], v[2:3], 0, s[50:51]
	global_load_dword v6, v[2:3], off nt
	v_lshl_add_u64 v[2:3], v[2:3], 0, s[50:51]
	global_load_dword v7, v[2:3], off nt
	v_lshl_add_u64 v[2:3], v[2:3], 0, s[50:51]
	global_load_dword v8, v[2:3], off nt
	v_lshl_add_u64 v[2:3], v[2:3], 0, s[50:51]
	global_load_dword v9, v[2:3], off nt
	v_lshl_add_u64 v[2:3], v[2:3], 0, s[50:51]
	global_load_dword v10, v[2:3], off nt
	v_lshl_add_u64 v[2:3], v[2:3], 0, s[50:51]
	global_load_dword v11, v[2:3], off nt
	v_lshl_add_u64 v[2:3], v[2:3], 0, s[50:51]
	global_load_dword v12, v[2:3], off nt
	v_lshl_add_u64 v[2:3], v[2:3], 0, s[50:51]
	global_load_dword v13, v[2:3], off nt
	v_lshl_add_u64 v[2:3], v[2:3], 0, s[50:51]
	global_load_dword v14, v[2:3], off nt
	v_lshl_add_u64 v[2:3], v[2:3], 0, s[50:51]
	global_load_dword v15, v[2:3], off nt
	v_lshl_add_u64 v[2:3], v[2:3], 0, s[50:51]
	global_load_dword v16, v[2:3], off nt
	v_lshl_add_u64 v[2:3], v[2:3], 0, s[50:51]
	global_load_dword v17, v[2:3], off nt
	v_lshl_add_u64 v[2:3], v[2:3], 0, s[50:51]
	global_load_dword v18, v[2:3], off nt
	v_lshl_add_u64 v[2:3], v[2:3], 0, s[50:51]
	global_load_dword v19, v[2:3], off nt
	v_or_b32_e32 v20, s9, v93
	s_movk_i32 s9, 0x104
	v_mad_u32_u24 v20, v20, s9, v95
	v_lshl_add_u64 v[2:3], v[2:3], 0, s[50:51]
	s_movk_i32 s9, 0x80
	s_and_b64 vcc, exec, s[6:7]
	s_mov_b64 s[6:7], 0
	s_waitcnt vmcnt(0)
	ds_write_b32 v20, v4
	ds_write_b32 v20, v5 offset:2080
	ds_write_b32 v20, v6 offset:4160
	ds_write_b32 v20, v7 offset:6240
	ds_write_b32 v20, v8 offset:8320
	ds_write_b32 v20, v9 offset:10400
	ds_write_b32 v20, v10 offset:12480
	ds_write_b32 v20, v11 offset:14560
	ds_write_b32 v20, v12 offset:16640
	ds_write_b32 v20, v13 offset:18720
	ds_write_b32 v20, v14 offset:20800
	ds_write_b32 v20, v15 offset:22880
	ds_write_b32 v20, v16 offset:24960
	ds_write_b32 v20, v17 offset:27040
	ds_write_b32 v20, v18 offset:29120
	ds_write_b32 v20, v19 offset:31200
	s_cbranch_vccnz .LBB0_326
	s_waitcnt lgkmcnt(0)
	s_barrier
	ds_read2_b32 v[8:9], v99 offset1:32
	v_add_u32_e32 v2, 0x400, v100
	ds_read2_b32 v[10:11], v2 offset0:4 offset1:36
	ds_read2_b32 v[12:13], v99 offset0:65 offset1:97
	ds_read2_b32 v[14:15], v2 offset0:69 offset1:101
	ds_read2_b32 v[16:17], v99 offset0:130 offset1:162
	ds_read2_b32 v[18:19], v2 offset0:134 offset1:166
	ds_read2_b32 v[20:21], v99 offset0:195 offset1:227
	ds_read2_b32 v[22:23], v2 offset0:199 offset1:231
	s_lshl_b32 s6, s8, 1
	s_add_u32 s4, s4, s6
	s_addc_u32 s5, s5, 0
	v_mov_b32_e32 v85, v73
	s_waitcnt lgkmcnt(5)
	v_cvt_pk_bf16_f32 v2, v8, v12
	v_or_b32_e32 v8, s18, v97
	v_lshl_add_u64 v[6:7], s[4:5], 0, v[84:85]
	v_mul_u32_u24_e32 v72, s27, v8
	s_waitcnt lgkmcnt(1)
	v_cvt_pk_bf16_f32 v3, v16, v20
	v_cvt_pk_bf16_f32 v4, v10, v14
	s_waitcnt lgkmcnt(0)
	v_cvt_pk_bf16_f32 v5, v18, v22
	v_lshl_add_u64 v[24:25], v[72:73], 1, v[6:7]
	global_store_dwordx4 v[24:25], v[2:5], off
	v_add_u32_e32 v8, 0x400, v103
	ds_read2_b32 v[2:3], v102 offset1:65
	ds_read2_b32 v[4:5], v8 offset0:4 offset1:69
	ds_read2_b32 v[24:25], v102 offset0:130 offset1:195
	ds_read2_b32 v[26:27], v8 offset0:134 offset1:199
	v_or_b32_e32 v8, s18, v101
	v_mul_u32_u24_e32 v72, s27, v8
	v_or_b32_e32 v8, s18, v104
	s_waitcnt lgkmcnt(3)
	v_cvt_pk_bf16_f32 v2, v2, v3
	s_waitcnt lgkmcnt(1)
	v_cvt_pk_bf16_f32 v3, v24, v25
	v_cvt_pk_bf16_f32 v4, v4, v5
	s_waitcnt lgkmcnt(0)
	v_cvt_pk_bf16_f32 v5, v26, v27
	v_lshl_add_u64 v[24:25], v[72:73], 1, v[6:7]
	v_mul_u32_u24_e32 v72, s27, v8
	global_store_dwordx4 v[24:25], v[2:5], off
	v_add_u32_e32 v10, 0x400, v107
	s_nop 0
	v_cvt_pk_bf16_f32 v2, v9, v13
	v_cvt_pk_bf16_f32 v3, v17, v21
	v_cvt_pk_bf16_f32 v4, v11, v15
	v_cvt_pk_bf16_f32 v5, v19, v23
	v_lshl_add_u64 v[8:9], v[72:73], 1, v[6:7]
	global_store_dwordx4 v[8:9], v[2:5], off
	ds_read2_b32 v[2:3], v106 offset1:65
	ds_read2_b32 v[4:5], v10 offset0:4 offset1:69
	ds_read2_b32 v[8:9], v106 offset0:130 offset1:195
	ds_read2_b32 v[10:11], v10 offset0:134 offset1:199
	s_waitcnt lgkmcnt(2)
	v_cvt_pk_bf16_f32 v4, v4, v5
	v_cvt_pk_bf16_f32 v2, v2, v3
	s_waitcnt lgkmcnt(1)
	v_cvt_pk_bf16_f32 v3, v8, v9
	v_add_u32_e32 v8, s18, v105
	v_mul_hi_u32_u24_e32 v9, s27, v8
	v_mul_u32_u24_e32 v8, s27, v8
	s_waitcnt lgkmcnt(0)
	v_cvt_pk_bf16_f32 v5, v10, v11
	v_lshl_add_u64 v[6:7], v[8:9], 1, v[6:7]
	global_store_dwordx4 v[6:7], v[2:5], off
	s_barrier

.LBB0_329:
	s_ashr_i32 s60, s26, 2
	s_and_b32 s18, s25, 3
	s_and_saveexec_b64 s[62:63], s[0:1]
	s_cbranch_execz .LBB0_344
	s_ashr_i32 s61, s60, 31
	v_readlane_b32 s80, v254, 5
	s_lshl_b64 s[4:5], s[60:61], 2
	v_readlane_b32 s92, v254, 17
	v_readlane_b32 s93, v254, 18
	s_add_u32 s4, s92, s4
	s_addc_u32 s5, s93, s5
	global_load_dword v8, v73, s[4:5] nt
	v_lshl_or_b32 v2, s60, 6, v1
	v_ashrrev_i32_e32 v3, 31, v2
	v_readlane_b32 s90, v254, 15
	v_readlane_b32 s91, v254, 16
	v_lshlrev_b64 v[6:7], 2, v[2:3]
	v_readlane_b32 s88, v254, 13
	v_lshl_add_u64 v[4:5], s[90:91], 0, v[6:7]
	global_load_dword v4, v[4:5], off nt
	v_readlane_b32 s89, v254, 14
	v_readlane_b32 s84, v254, 9
	v_readlane_b32 s85, v254, 10
	v_lshl_add_u64 v[6:7], s[88:89], 0, v[6:7]
	global_load_dword v6, v[6:7], off nt
	s_brev_b32 s4, 18
	v_readlane_b32 s81, v254, 6
	v_readlane_b32 s82, v254, 7
	v_readlane_b32 s83, v254, 8
	v_readlane_b32 s86, v254, 11
	v_readlane_b32 s87, v254, 12
	v_readlane_b32 s94, v254, 19
	v_readlane_b32 s95, v254, 20
	s_waitcnt vmcnt(0)
	v_mul_f32_e32 v5, 0x3fb8aa3b, v8
	v_fma_f32 v7, v8, s96, -v5
	v_rndne_f32_e32 v9, v5
	v_fmac_f32_e32 v7, 0x32a5705f, v8
	v_sub_f32_e32 v5, v5, v9
	v_add_f32_e32 v5, v5, v7
	v_cvt_i32_f32_e32 v9, v9
	v_exp_f32_e32 v5, v5
	v_cmp_ngt_f32_e32 vcc, s97, v8
	v_ldexp_f32 v5, v5, v9
	s_nop 0
	v_cndmask_b32_e32 v5, 0, v5, vcc
	v_cmp_nlt_f32_e32 vcc, s14, v8
	s_nop 1
	v_cndmask_b32_e32 v8, v124, v5, vcc
	v_mul_f32_e32 v5, v8, v4
	v_and_b32_e32 v7, 0x7fffffff, v5
	v_lshrrev_b32_e32 v9, 23, v7
	v_and_b32_e32 v10, 0x7fffff, v7
	v_cmp_nlt_f32_e64 s[84:85], |v5|, s4
	v_add_u32_e32 v12, 0xffffff88, v9
	v_or_b32_e32 v11, 0x800000, v10
	s_and_saveexec_b64 s[4:5], s[84:85]
	s_xor_b64 s[26:27], exec, s[4:5]
	s_cbranch_execz .LBB0_332
	v_mad_u64_u32 v[14:15], s[8:9], v11, s15, 0
	v_mov_b32_e32 v72, v15
	v_mad_u64_u32 v[16:17], s[8:9], v11, s12, v[72:73]
	v_mov_b32_e32 v72, v17
	v_mad_u64_u32 v[18:19], s[8:9], v11, s13, v[72:73]
	v_cmp_lt_u32_e32 vcc, 63, v12
	v_mov_b32_e32 v72, v19
	v_mad_u64_u32 v[20:21], s[8:9], v11, s16, v[72:73]
	v_cndmask_b32_e32 v9, 0, v125, vcc
	v_add_u32_e32 v9, v9, v12
	v_mov_b32_e32 v72, v21
	v_cmp_lt_u32_e64 s[4:5], 31, v9
	v_mad_u64_u32 v[22:23], s[8:9], v11, s17, v[72:73]
	s_nop 0
	v_cndmask_b32_e64 v10, 0, v126, s[4:5]
	v_mov_b32_e32 v72, v23
	v_add_u32_e32 v9, v10, v9
	v_mad_u64_u32 v[24:25], s[8:9], v11, s20, v[72:73]
	v_cmp_lt_u32_e64 s[6:7], 31, v9
	v_mov_b32_e32 v72, v25
	v_mad_u64_u32 v[26:27], s[8:9], v11, s21, v[72:73]
	v_cndmask_b32_e64 v10, 0, v126, s[6:7]
	v_add_u32_e32 v9, v10, v9
	v_cndmask_b32_e32 v10, v24, v20, vcc
	v_cndmask_b32_e32 v13, v26, v22, vcc
	v_cndmask_b32_e32 v17, v27, v24, vcc
	v_cndmask_b32_e64 v15, v13, v10, s[4:5]
	v_cndmask_b32_e64 v13, v17, v13, s[4:5]
	v_cndmask_b32_e32 v17, v22, v18, vcc
	v_cndmask_b32_e64 v10, v10, v17, s[4:5]
	v_cndmask_b32_e64 v13, v13, v15, s[6:7]
	v_cndmask_b32_e64 v15, v15, v10, s[6:7]
	v_sub_u32_e32 v19, 32, v9
	v_alignbit_b32 v21, v13, v15, v19
	v_cmp_eq_u32_e64 s[8:9], 0, v9
	v_cndmask_b32_e32 v14, v18, v14, vcc
	s_nop 0
	v_cndmask_b32_e64 v9, v21, v13, s[8:9]
	v_cndmask_b32_e32 v13, v20, v16, vcc
	v_cndmask_b32_e64 v16, v17, v13, s[4:5]
	v_cndmask_b32_e64 v10, v10, v16, s[6:7]
	v_alignbit_b32 v17, v15, v10, v19
	v_cndmask_b32_e64 v13, v13, v14, s[4:5]
	v_cndmask_b32_e64 v15, v17, v15, s[8:9]
	v_bfe_u32 v21, v9, 29, 1
	v_cndmask_b32_e64 v13, v16, v13, s[6:7]
	v_alignbit_b32 v17, v9, v15, 30
	v_sub_u32_e32 v22, 0, v21
	v_alignbit_b32 v14, v10, v13, v19
	v_xor_b32_e32 v17, v17, v22
	v_cndmask_b32_e64 v10, v14, v10, s[8:9]
	v_alignbit_b32 v14, v15, v10, 30
	v_ffbh_u32_e32 v15, v17
	v_min_u32_e32 v15, 32, v15
	v_alignbit_b32 v10, v10, v13, 30
	v_xor_b32_e32 v14, v14, v22
	v_sub_u32_e32 v16, 31, v15
	v_xor_b32_e32 v10, v10, v22
	v_alignbit_b32 v17, v17, v14, v16
	v_alignbit_b32 v10, v14, v10, v16
	v_alignbit_b32 v13, v17, v10, 9
	v_ffbh_u32_e32 v14, v13
	v_min_u32_e32 v14, 32, v14
	v_lshrrev_b32_e32 v20, 29, v9
	v_not_b32_e32 v16, v14
	v_alignbit_b32 v10, v13, v10, v16
	v_lshlrev_b32_e32 v13, 31, v20
	v_or_b32_e32 v16, 0x33000000, v13
	v_add_lshl_u32 v14, v14, v15, 23
	v_lshrrev_b32_e32 v10, 9, v10
	v_sub_u32_e32 v14, v16, v14
	v_or_b32_e32 v13, 0.5, v13
	v_lshlrev_b32_e32 v15, 23, v15
	v_or_b32_e32 v10, v14, v10
	v_lshrrev_b32_e32 v14, 9, v17
	v_sub_u32_e32 v13, v13, v15
	v_or_b32_e32 v13, v14, v13
	v_mul_f32_e32 v14, 0x3fc90fda, v13
	v_fma_f32 v15, v13, s22, -v14
	v_fmac_f32_e32 v15, 0x33a22168, v13
	v_fmac_f32_e32 v15, 0x3fc90fda, v10
	v_lshrrev_b32_e32 v9, 30, v9
	v_add_f32_e32 v10, v14, v15
	v_add_u32_e32 v9, v21, v9

.LBB0_345:
	global_load_dword v8, v[2:3], off nt
	global_load_dword v9, v[4:5], off nt
	v_add_co_u32_e32 v6, vcc, 0x200, v6
	s_xor_b64 s[6:7], vcc, -1
	s_and_b64 s[6:7], exec, s[6:7]
	v_lshl_add_u64 v[2:3], v[2:3], 0, s[58:59]
	v_lshl_add_u64 v[4:5], v[4:5], 0, s[58:59]
	s_or_b64 s[4:5], s[6:7], s[4:5]
	s_waitcnt vmcnt(0)
	ds_write_b64 v7, v[8:9]
	v_add_u32_e32 v7, 0x1000, v7
	s_andn2_b64 exec, exec, s[4:5]
	s_cbranch_execnz .LBB0_345
	s_or_b64 exec, exec, s[4:5]
	s_lshl_b32 s9, s18, 2
	v_or_b32_e32 v2, s9, v109
	v_cmp_eq_u32_e32 vcc, v2, v110
	v_lshl_or_b32 v2, s60, 4, v2
	v_readlane_b32 s80, v254, 21
	s_and_b32 s8, s2, 3
	v_ashrrev_i32_e32 v3, 31, v2
	v_readlane_b32 s86, v254, 27
	v_readlane_b32 s87, v254, 28
	v_lshl_add_u32 v4, s8, 11, v117
	s_mov_b32 s6, 0
	v_lshl_add_u64 v[2:3], v[2:3], 2, s[86:87]
	v_mov_b32_e32 v5, v119
	s_waitcnt lgkmcnt(0)
	s_barrier
	v_readlane_b32 s81, v254, 22
	v_readlane_b32 s82, v254, 23
	v_readlane_b32 s83, v254, 24
	v_readlane_b32 s84, v254, 25
	v_readlane_b32 s85, v254, 26
	v_readlane_b32 s88, v254, 29
	v_readlane_b32 s89, v254, 30
	v_readlane_b32 s90, v254, 31
	v_readlane_b32 s91, v254, 32
	v_readlane_b32 s92, v254, 33
	v_readlane_b32 s93, v254, 34
	v_readlane_b32 s94, v254, 35
	v_readlane_b32 s95, v254, 36
	s_branch .LBB0_348

.LBB0_349:
	v_add_u32_e32 v9, s4, v4
	ds_read2_b64 v[10:13], v6 offset1:33
	ds_read_b128 v[14:17], v9
	ds_read_b128 v[18:21], v9 offset:16
	ds_read2_b64 v[22:25], v7 offset1:16
	s_add_i32 s4, s4, 32
	s_cmpk_eq_i32 s4, 0x200
	s_waitcnt lgkmcnt(2)
	v_pk_mul_f32 v[26:27], v[14:15], v[10:11] op_sel:[1,1] op_sel_hi:[0,1]
	v_pk_fma_f32 v[28:29], v[14:15], v[10:11], v[26:27] neg_lo:[0,0,1] neg_hi:[0,0,1]
	v_pk_fma_f32 v[10:11], v[14:15], v[10:11], v[26:27] op_sel_hi:[1,0,1]
	s_nop 0
	v_mov_b32_e32 v29, v11
	s_waitcnt lgkmcnt(0)
	v_pk_mul_f32 v[10:11], v[22:23], v[28:29]
	s_nop 0
	v_sub_f32_e32 v9, v10, v11
	v_add_f32_e32 v14, v8, v9
	v_pk_mul_f32 v[8:9], v[16:17], v[12:13] op_sel:[1,1] op_sel_hi:[0,1]
	v_pk_fma_f32 v[10:11], v[16:17], v[12:13], v[8:9] neg_lo:[0,0,1] neg_hi:[0,0,1]
	v_pk_fma_f32 v[8:9], v[16:17], v[12:13], v[8:9] op_sel_hi:[1,0,1]
	s_nop 0
	v_mov_b32_e32 v11, v9
	v_pk_mul_f32 v[8:9], v[24:25], v[10:11]
	s_nop 0
	v_sub_f32_e32 v8, v8, v9
	v_add_f32_e32 v24, v14, v8
	ds_read2_b64 v[8:11], v6 offset0:66 offset1:99
	ds_read2_b64 v[12:15], v7 offset0:32 offset1:48
	v_add_u32_e32 v7, 0x200, v7
	v_add_u32_e32 v6, 0x420, v6
	s_waitcnt lgkmcnt(1)
	v_pk_mul_f32 v[16:17], v[18:19], v[8:9] op_sel:[1,1] op_sel_hi:[0,1]
	v_pk_fma_f32 v[22:23], v[18:19], v[8:9], v[16:17] neg_lo:[0,0,1] neg_hi:[0,0,1]
	v_pk_fma_f32 v[8:9], v[18:19], v[8:9], v[16:17] op_sel_hi:[1,0,1]
	s_nop 0
	v_mov_b32_e32 v23, v9
	s_waitcnt lgkmcnt(0)
	v_pk_mul_f32 v[8:9], v[12:13], v[22:23]
	s_nop 0
	v_sub_f32_e32 v8, v8, v9
	v_add_f32_e32 v16, v24, v8
	v_pk_mul_f32 v[8:9], v[20:21], v[10:11] op_sel:[1,1] op_sel_hi:[0,1]
	v_pk_fma_f32 v[12:13], v[20:21], v[10:11], v[8:9] neg_lo:[0,0,1] neg_hi:[0,0,1]
	v_pk_fma_f32 v[8:9], v[20:21], v[10:11], v[8:9] op_sel_hi:[1,0,1]
	s_nop 0
	v_mov_b32_e32 v13, v9
	v_pk_mul_f32 v[8:9], v[14:15], v[12:13]
	s_nop 0
	v_sub_f32_e32 v8, v8, v9
	v_add_f32_e32 v8, v16, v8
	s_cbranch_scc0 .LBB0_349
	v_lshl_add_u32 v6, s6, 9, v1
	v_cmp_gt_u32_e64 s[4:5], 64, v6
	s_and_b64 s[18:19], vcc, s[4:5]
	s_and_saveexec_b64 s[4:5], s[18:19]
	s_cbranch_execz .LBB0_347
	global_load_dword v7, v[2:3], off nt
	s_waitcnt vmcnt(0)
	v_add_f32_e32 v8, v8, v7
	s_branch .LBB0_347

.LBB0_501:
	global_load_dword v4, v[2:3], off nt
	v_lshl_add_u64 v[2:3], v[2:3], 0, s[6:7]
	global_load_dword v5, v[2:3], off nt
	v_lshl_add_u64 v[2:3], v[2:3], 0, s[6:7]
	global_load_dword v6, v[2:3], off nt
	v_lshl_add_u64 v[2:3], v[2:3], 0, s[6:7]
	global_load_dword v7, v[2:3], off nt
	v_lshl_add_u64 v[2:3], v[2:3], 0, s[6:7]
	global_load_dword v8, v[2:3], off nt
	v_lshl_add_u64 v[2:3], v[2:3], 0, s[6:7]
	global_load_dword v9, v[2:3], off nt
	v_lshl_add_u64 v[2:3], v[2:3], 0, s[6:7]
	global_load_dword v10, v[2:3], off nt
	v_lshl_add_u64 v[2:3], v[2:3], 0, s[6:7]
	global_load_dword v15, v[2:3], off nt
	v_lshl_add_u64 v[2:3], v[2:3], 0, s[6:7]
	global_load_dword v17, v[2:3], off nt
	v_lshl_add_u64 v[2:3], v[2:3], 0, s[6:7]
	global_load_dword v18, v[2:3], off nt
	v_lshl_add_u64 v[2:3], v[2:3], 0, s[6:7]
	global_load_dword v19, v[2:3], off nt
	v_lshl_add_u64 v[2:3], v[2:3], 0, s[6:7]
	global_load_dword v20, v[2:3], off nt
	v_lshl_add_u64 v[2:3], v[2:3], 0, s[6:7]
	global_load_dword v21, v[2:3], off nt
	v_lshl_add_u64 v[2:3], v[2:3], 0, s[6:7]
	global_load_dword v22, v[2:3], off nt
	v_lshl_add_u64 v[2:3], v[2:3], 0, s[6:7]
	global_load_dword v23, v[2:3], off nt
	v_lshl_add_u64 v[2:3], v[2:3], 0, s[6:7]
	global_load_dword v53, v[2:3], off nt
	v_or_b32_e32 v54, s10, v24
	s_movk_i32 s10, 0x104
	v_mad_u32_u24 v54, v54, s10, v25
	v_lshl_add_u64 v[2:3], v[2:3], 0, s[6:7]
	s_movk_i32 s10, 0x80
	s_and_b64 vcc, exec, s[8:9]
	s_mov_b64 s[8:9], 0
	s_waitcnt vmcnt(15)
	ds_write_b32 v54, v4
	s_waitcnt vmcnt(14)
	ds_write_b32 v54, v5 offset:2080
	s_waitcnt vmcnt(13)
	ds_write_b32 v54, v6 offset:4160
	s_waitcnt vmcnt(12)
	ds_write_b32 v54, v7 offset:6240
	s_waitcnt vmcnt(11)
	ds_write_b32 v54, v8 offset:8320
	s_waitcnt vmcnt(10)
	ds_write_b32 v54, v9 offset:10400
	s_waitcnt vmcnt(9)
	ds_write_b32 v54, v10 offset:12480
	s_waitcnt vmcnt(8)
	ds_write_b32 v54, v15 offset:14560
	s_waitcnt vmcnt(7)
	ds_write_b32 v54, v17 offset:16640
	s_waitcnt vmcnt(6)
	ds_write_b32 v54, v18 offset:18720
	s_waitcnt vmcnt(5)
	ds_write_b32 v54, v19 offset:20800
	s_waitcnt vmcnt(4)
	ds_write_b32 v54, v20 offset:22880
	s_waitcnt vmcnt(3)
	ds_write_b32 v54, v21 offset:24960
	s_waitcnt vmcnt(2)
	ds_write_b32 v54, v22 offset:27040
	s_waitcnt vmcnt(1)
	ds_write_b32 v54, v23 offset:29120
	s_waitcnt vmcnt(0)
	ds_write_b32 v54, v53 offset:31200
	s_cbranch_vccnz .LBB0_501
	s_waitcnt lgkmcnt(0)
	s_barrier
	ds_read2_b32 v[6:7], v26 offset1:32
	v_add_u32_e32 v2, 0x400, v27
	ds_read2_b32 v[8:9], v2 offset0:4 offset1:36
	ds_read2_b32 v[18:19], v26 offset0:65 offset1:97
	ds_read2_b32 v[20:21], v2 offset0:69 offset1:101
	ds_read2_b32 v[22:23], v26 offset0:130 offset1:162
	ds_read2_b32 v[54:55], v26 offset0:195 offset1:227
	ds_read2_b32 v[56:57], v2 offset0:134 offset1:166
	ds_read2_b32 v[58:59], v2 offset0:199 offset1:231
	s_lshl_b32 s6, s19, 1
	ds_read2_b32 v[64:65], v29 offset1:65
	s_waitcnt lgkmcnt(6)
	v_cvt_pk_bf16_f32 v2, v6, v18
	v_or_b32_e32 v6, s18, v142
	v_mul_u32_u24_e32 v10, s27, v6
	v_add_u32_e32 v6, 0x400, v30
	ds_read2_b32 v[66:67], v29 offset0:130 offset1:195
	ds_read2_b32 v[68:69], v6 offset0:4 offset1:69
	ds_read2_b32 v[70:71], v6 offset0:134 offset1:199
	s_add_u32 s4, s4, s6
	s_addc_u32 s5, s5, 0
	v_mov_b32_e32 v17, v11
	v_lshl_add_u64 v[60:61], s[4:5], 0, v[16:17]
	v_or_b32_e32 v6, s18, v28
	s_waitcnt lgkmcnt(6)
	v_cvt_pk_bf16_f32 v3, v22, v54
	v_cvt_pk_bf16_f32 v4, v8, v20
	s_waitcnt lgkmcnt(4)
	v_cvt_pk_bf16_f32 v5, v56, v58
	v_lshl_add_u64 v[62:63], v[10:11], 1, v[60:61]
	v_mul_u32_u24_e32 v10, s27, v6
	global_store_dwordx4 v[62:63], v[2:5], off
	v_lshl_add_u64 v[62:63], v[10:11], 1, v[60:61]
	v_or_b32_e32 v6, s18, v31
	s_waitcnt lgkmcnt(3)
	v_cvt_pk_bf16_f32 v2, v64, v65
	s_waitcnt lgkmcnt(2)
	v_cvt_pk_bf16_f32 v3, v66, v67
	s_waitcnt lgkmcnt(1)
	v_cvt_pk_bf16_f32 v4, v68, v69
	s_waitcnt lgkmcnt(0)
	v_cvt_pk_bf16_f32 v5, v70, v71
	global_store_dwordx4 v[62:63], v[2:5], off
	v_mul_u32_u24_e32 v10, s27, v6
	s_mov_b64 s[4:5], 0
	v_cvt_pk_bf16_f32 v2, v7, v19
	v_cvt_pk_bf16_f32 v3, v23, v55
	v_cvt_pk_bf16_f32 v4, v9, v21
	v_lshl_add_u64 v[6:7], v[10:11], 1, v[60:61]
	ds_read2_b32 v[8:9], v33 offset1:65
	v_add_u32_e32 v10, 0x400, v34
	ds_read2_b32 v[18:19], v33 offset0:130 offset1:195
	ds_read2_b32 v[20:21], v10 offset0:4 offset1:69
	ds_read2_b32 v[22:23], v10 offset0:134 offset1:199
	v_cvt_pk_bf16_f32 v5, v57, v59
	global_store_dwordx4 v[6:7], v[2:5], off
	v_add_u32_e32 v6, s18, v32
	v_mul_hi_u32_u24_e32 v7, s27, v6
	v_mul_u32_u24_e32 v6, s27, v6
	s_waitcnt lgkmcnt(3)
	v_cvt_pk_bf16_f32 v2, v8, v9
	s_waitcnt lgkmcnt(2)
	v_cvt_pk_bf16_f32 v3, v18, v19
	s_waitcnt lgkmcnt(1)
	v_cvt_pk_bf16_f32 v4, v20, v21
	s_waitcnt lgkmcnt(0)
	v_cvt_pk_bf16_f32 v5, v22, v23
	v_lshl_add_u64 v[6:7], v[6:7], 1, v[60:61]
	global_store_dwordx4 v[6:7], v[2:5], off
	s_barrier
.LBB0_503:
	s_and_b64 vcc, exec, s[4:5]
	s_cbranch_vccz .LBB0_459
	s_ashr_i32 s54, s26, 2
	s_and_b32 s18, s24, 3
	s_and_saveexec_b64 s[56:57], s[0:1]
	s_cbranch_execz .LBB0_519
	s_ashr_i32 s55, s54, 31
	v_readlane_b32 s36, v254, 5
	s_lshl_b64 s[4:5], s[54:55], 2
	v_readlane_b32 s48, v254, 17
	v_readlane_b32 s49, v254, 18
	s_add_u32 s4, s48, s4
	s_addc_u32 s5, s49, s5
	global_load_dword v8, v11, s[4:5] nt
	v_lshl_or_b32 v2, s54, 6, v1
	v_ashrrev_i32_e32 v3, 31, v2
	v_readlane_b32 s46, v254, 15
	v_readlane_b32 s47, v254, 16
	v_lshlrev_b64 v[6:7], 2, v[2:3]
	v_readlane_b32 s44, v254, 13
	v_lshl_add_u64 v[4:5], s[46:47], 0, v[6:7]
	global_load_dword v4, v[4:5], off nt
	v_readlane_b32 s45, v254, 14
	s_brev_b32 s4, 18
	v_readlane_b32 s37, v254, 6
	v_lshl_add_u64 v[6:7], s[44:45], 0, v[6:7]
	global_load_dword v6, v[6:7], off nt
	v_readlane_b32 s38, v254, 7
	v_readlane_b32 s39, v254, 8
	v_readlane_b32 s40, v254, 9
	v_readlane_b32 s41, v254, 10
	v_readlane_b32 s42, v254, 11
	v_readlane_b32 s43, v254, 12
	v_readlane_b32 s50, v254, 19
	v_readlane_b32 s51, v254, 20
	s_waitcnt vmcnt(2)
	v_mul_f32_e32 v5, 0x3fb8aa3b, v8
	v_fma_f32 v7, v8, s25, -v5
	v_rndne_f32_e32 v9, v5
	v_fmac_f32_e32 v7, 0x32a5705f, v8
	v_sub_f32_e32 v5, v5, v9
	v_add_f32_e32 v5, v5, v7
	v_cvt_i32_f32_e32 v9, v9
	v_exp_f32_e32 v5, v5
	v_cmp_ngt_f32_e32 vcc, s60, v8
	v_ldexp_f32 v5, v5, v9
	s_nop 0
	v_cndmask_b32_e32 v5, 0, v5, vcc
	v_cmp_nlt_f32_e32 vcc, s61, v8
	s_nop 1
	v_cndmask_b32_e32 v8, v49, v5, vcc
	s_waitcnt vmcnt(1)
	v_mul_f32_e32 v5, v8, v4
	v_and_b32_e32 v7, 0x7fffffff, v5
	v_lshrrev_b32_e32 v9, 23, v7
	v_and_b32_e32 v10, 0x7fffff, v7
	v_cmp_nlt_f32_e64 s[58:59], |v5|, s4
	v_add_u32_e32 v18, 0xffffff88, v9
	v_or_b32_e32 v17, 0x800000, v10
	s_and_saveexec_b64 s[4:5], s[58:59]
	s_xor_b64 s[26:27], exec, s[4:5]
	s_cbranch_execz .LBB0_507
	v_cmp_lt_u32_e32 vcc, 63, v18
	v_mad_u64_u32 v[20:21], s[8:9], v17, s62, 0
	s_nop 0
	v_cndmask_b32_e32 v9, 0, v50, vcc
	v_add_u32_e32 v9, v9, v18
	v_cmp_lt_u32_e64 s[4:5], 31, v9
	s_nop 1
	v_cndmask_b32_e64 v10, 0, v51, s[4:5]
	v_add_u32_e32 v9, v10, v9
	v_cmp_lt_u32_e64 s[6:7], 31, v9
	s_nop 1
	v_cndmask_b32_e64 v10, 0, v51, s[6:7]
	v_add_u32_e32 v9, v10, v9
	v_mov_b32_e32 v10, v21
	v_mad_u64_u32 v[22:23], s[8:9], v17, s63, v[10:11]
	v_mov_b32_e32 v10, v23
	v_mad_u64_u32 v[54:55], s[8:9], v17, s81, v[10:11]
	v_mov_b32_e32 v10, v55
	v_mad_u64_u32 v[56:57], s[8:9], v17, s82, v[10:11]
	v_mov_b32_e32 v10, v57
	v_mad_u64_u32 v[58:59], s[8:9], v17, s83, v[10:11]
	v_mov_b32_e32 v10, v59
	v_mad_u64_u32 v[60:61], s[8:9], v17, s84, v[10:11]
	v_mov_b32_e32 v10, v61
	v_mad_u64_u32 v[62:63], s[8:9], v17, s85, v[10:11]
	v_cndmask_b32_e32 v15, v60, v56, vcc
	v_cndmask_b32_e32 v10, v62, v58, vcc
	v_cndmask_b32_e32 v21, v63, v60, vcc
	v_cndmask_b32_e64 v19, v10, v15, s[4:5]
	v_cndmask_b32_e64 v10, v21, v10, s[4:5]
	v_cndmask_b32_e32 v21, v58, v54, vcc
	v_cndmask_b32_e64 v15, v15, v21, s[4:5]
	v_cndmask_b32_e64 v10, v10, v19, s[6:7]
	v_cndmask_b32_e64 v19, v19, v15, s[6:7]
	v_sub_u32_e32 v23, 32, v9
	v_alignbit_b32 v53, v10, v19, v23
	v_cmp_eq_u32_e64 s[8:9], 0, v9
	v_cndmask_b32_e32 v20, v54, v20, vcc
	s_nop 0
	v_cndmask_b32_e64 v9, v53, v10, s[8:9]
	v_cndmask_b32_e32 v10, v56, v22, vcc
	v_cndmask_b32_e64 v21, v21, v10, s[4:5]
	v_cndmask_b32_e64 v15, v15, v21, s[6:7]
	v_alignbit_b32 v22, v19, v15, v23
	v_cndmask_b32_e64 v19, v22, v19, s[8:9]
	v_bfe_u32 v55, v9, 29, 1
	v_cndmask_b32_e64 v10, v10, v20, s[4:5]
	v_alignbit_b32 v22, v9, v19, 30
	v_sub_u32_e32 v56, 0, v55
	v_cndmask_b32_e64 v10, v21, v10, s[6:7]
	v_xor_b32_e32 v22, v22, v56
	v_alignbit_b32 v20, v15, v10, v23
	v_cndmask_b32_e64 v15, v20, v15, s[8:9]
	v_ffbh_u32_e32 v20, v22
	v_alignbit_b32 v19, v19, v15, 30
	v_min_u32_e32 v20, 32, v20
	v_alignbit_b32 v10, v15, v10, 30
	v_xor_b32_e32 v19, v19, v56
	v_sub_u32_e32 v21, 31, v20
	v_xor_b32_e32 v10, v10, v56
	v_alignbit_b32 v22, v22, v19, v21
	v_alignbit_b32 v10, v19, v10, v21
	v_alignbit_b32 v15, v22, v10, 9
	v_ffbh_u32_e32 v19, v15
	v_min_u32_e32 v19, 32, v19
	v_lshrrev_b32_e32 v53, 29, v9
	v_not_b32_e32 v21, v19
	v_alignbit_b32 v10, v15, v10, v21
	v_lshlrev_b32_e32 v15, 31, v53
	v_or_b32_e32 v21, 0x33000000, v15
	v_add_lshl_u32 v19, v19, v20, 23
	v_lshrrev_b32_e32 v10, 9, v10
	v_sub_u32_e32 v19, v21, v19
	v_or_b32_e32 v15, 0.5, v15
	v_lshlrev_b32_e32 v20, 23, v20
	v_or_b32_e32 v10, v19, v10
	v_lshrrev_b32_e32 v19, 9, v22
	v_sub_u32_e32 v15, v15, v20
	v_or_b32_e32 v15, v19, v15
	v_mul_f32_e32 v19, 0x3fc90fda, v15
	v_fma_f32 v20, v15, s86, -v19
	v_fmac_f32_e32 v20, 0x33a22168, v15
	v_fmac_f32_e32 v20, 0x3fc90fda, v10
	v_lshrrev_b32_e32 v9, 30, v9
	v_add_f32_e32 v15, v19, v20
	v_add_u32_e32 v9, v55, v9

.LBB0_520:
	global_load_dword v8, v[2:3], off nt
	global_load_dword v9, v[4:5], off nt
	v_add_co_u32_e32 v6, vcc, 0x200, v6
	s_xor_b64 s[6:7], vcc, -1
	s_and_b64 s[6:7], exec, s[6:7]
	v_lshl_add_u64 v[2:3], v[2:3], 0, s[52:53]
	v_lshl_add_u64 v[4:5], v[4:5], 0, s[52:53]
	s_or_b64 s[4:5], s[6:7], s[4:5]
	s_waitcnt vmcnt(0)
	ds_write_b64 v7, v[8:9]
	v_add_u32_e32 v7, 0x1000, v7
	s_andn2_b64 exec, exec, s[4:5]
	s_cbranch_execnz .LBB0_520
	s_or_b64 exec, exec, s[4:5]
	s_lshl_b32 s9, s18, 2
	v_or_b32_e32 v2, s9, v36
	v_cmp_eq_u32_e32 vcc, v2, v228
	v_lshl_or_b32 v2, s54, 4, v2
	v_readlane_b32 s36, v254, 21
	s_and_b32 s8, s88, 3
	v_ashrrev_i32_e32 v3, 31, v2
	v_readlane_b32 s42, v254, 27
	v_readlane_b32 s43, v254, 28
	v_lshl_add_u32 v4, s8, 11, v43
	s_mov_b32 s6, 0
	v_lshl_add_u64 v[2:3], v[2:3], 2, s[42:43]
	v_mov_b32_e32 v5, v45
	s_waitcnt lgkmcnt(0)
	s_barrier
	v_readlane_b32 s37, v254, 22
	v_readlane_b32 s38, v254, 23
	v_readlane_b32 s39, v254, 24
	v_readlane_b32 s40, v254, 25
	v_readlane_b32 s41, v254, 26
	v_readlane_b32 s44, v254, 29
	v_readlane_b32 s45, v254, 30
	v_readlane_b32 s46, v254, 31
	v_readlane_b32 s47, v254, 32
	v_readlane_b32 s48, v254, 33
	v_readlane_b32 s49, v254, 34
	v_readlane_b32 s50, v254, 35
	v_readlane_b32 s51, v254, 36
	s_branch .LBB0_523

.LBB0_524:
	v_add_u32_e32 v9, s4, v4
	ds_read2_b64 v[18:21], v7 offset1:33
	ds_read2_b64 v[54:57], v8 offset1:16
	ds_read2_b64 v[58:61], v7 offset0:66 offset1:99
	ds_read2_b64 v[62:65], v8 offset0:32 offset1:48
	ds_read_b128 v[66:69], v9
	ds_read_b128 v[70:73], v9 offset:16
	s_add_i32 s4, s4, 32
	v_add_u32_e32 v8, 0x200, v8
	v_add_u32_e32 v7, 0x420, v7
	s_waitcnt lgkmcnt(1)
	v_pk_mul_f32 v[22:23], v[66:67], v[18:19] op_sel:[1,1] op_sel_hi:[0,1]
	v_pk_mul_f32 v[74:75], v[68:69], v[20:21] op_sel:[1,1] op_sel_hi:[0,1]
	v_pk_fma_f32 v[80:81], v[66:67], v[18:19], v[22:23] neg_lo:[0,0,1] neg_hi:[0,0,1]
	v_pk_fma_f32 v[18:19], v[66:67], v[18:19], v[22:23] op_sel_hi:[1,0,1]
	s_waitcnt lgkmcnt(0)
	v_pk_mul_f32 v[76:77], v[70:71], v[58:59] op_sel:[1,1] op_sel_hi:[0,1]
	v_pk_fma_f32 v[22:23], v[68:69], v[20:21], v[74:75] neg_lo:[0,0,1] neg_hi:[0,0,1]
	v_pk_fma_f32 v[20:21], v[68:69], v[20:21], v[74:75] op_sel_hi:[1,0,1]
	v_mov_b32_e32 v81, v19
	v_pk_mul_f32 v[78:79], v[72:73], v[60:61] op_sel:[1,1] op_sel_hi:[0,1]
	v_pk_fma_f32 v[66:67], v[70:71], v[58:59], v[76:77] neg_lo:[0,0,1] neg_hi:[0,0,1]
	v_pk_fma_f32 v[58:59], v[70:71], v[58:59], v[76:77] op_sel_hi:[1,0,1]
	v_mov_b32_e32 v23, v21
	v_pk_mul_f32 v[18:19], v[54:55], v[80:81]
	v_pk_fma_f32 v[68:69], v[72:73], v[60:61], v[78:79] neg_lo:[0,0,1] neg_hi:[0,0,1]
	v_pk_fma_f32 v[60:61], v[72:73], v[60:61], v[78:79] op_sel_hi:[1,0,1]
	v_mov_b32_e32 v67, v59
	v_pk_mul_f32 v[20:21], v[56:57], v[22:23]
	v_sub_f32_e32 v9, v18, v19
	v_mov_b32_e32 v69, v61
	v_pk_mul_f32 v[22:23], v[62:63], v[66:67]
	v_sub_f32_e32 v10, v20, v21
	v_add_f32_e32 v6, v6, v9
	v_pk_mul_f32 v[54:55], v[64:65], v[68:69]
	v_sub_f32_e32 v15, v22, v23
	v_add_f32_e32 v6, v6, v10
	v_sub_f32_e32 v17, v54, v55
	v_add_f32_e32 v6, v6, v15
	s_cmpk_eq_i32 s4, 0x200
	v_add_f32_e32 v6, v6, v17
	s_cbranch_scc0 .LBB0_524
	v_lshl_add_u32 v7, s6, 9, v1
	v_cmp_gt_u32_e64 s[4:5], 64, v7
	s_and_b64 s[10:11], vcc, s[4:5]
	s_and_saveexec_b64 s[4:5], s[10:11]
	s_cbranch_execz .LBB0_522
	global_load_dword v8, v[2:3], off nt
	s_waitcnt vmcnt(0)
	v_add_f32_e32 v6, v6, v8
	s_branch .LBB0_522
